# adds v_rcp_f32 in place of the IEEE 1.0f/x sequences in both attention finalizes, the two diffmix loops and the EpiUp row scale (all rounded to bf16 afterwards)
# speedup vs baseline: 1.0226x; 1.0065x over previous
; __device__ __forceinline__ void st_bf8(bf16* p, f32x4 a, f32x4 b) { u32x4 w; w.x = pk2(a[0], a[1]); w.y = pk2(a[2], a[3]); w.z = pk2(b[0], b[1]); w.w = pk2(b[2], b[3]); *(u32x4*)p = w; }
;     __device__ __forceinline__ void operator()(AccRef acc, const pg8::Unit& u, int wr, int wc, int fr, int fq) const {
;         const int c0 = u.pn * 256;
; #pragma unroll
;         for (int ai = 0; ai < 2; ++ai)
; #pragma unroll
;             for (int m = 0; m < 4; ++m) {
;                 const int row = u.pm * 256 + ai * 128 + wr * 64 + m * 16 + fr; const size_t rw = (size_t)row;
;                 const float rs2 = 1.0f / (SSQ[row] * (1.f / 1024.f) + EPSN);
; #pragma unroll
;                 for (int bj = 0; bj < 2; ++bj) {
;                     const int cl = bj * 128 + wc * 32 + 8 * fq; const f32x4 v0 = acc[ai][bj][m][0], v1 = acc[ai][bj][m][1];
;                     f32x4 r0, r1; r0[0] = fmaxf(v0[0], 0.f); r0[1] = fmaxf(v0[1], 0.f); r0[2] = fmaxf(v0[2], 0.f); r0[3] = fmaxf(v0[3], 0.f); r1[0] = fmaxf(v1[0], 0.f); r1[1] = fmaxf(v1[1], 0.f); r1[2] = fmaxf(v1[2], 0.f); r1[3] = fmaxf(v1[3], 0.f);
;                     st_bf8(U + rw * 4096 + c0 + cl, r0 * r0 * rs2, r1 * r1 * rs2);
;                 }
;                 asm volatile("" ::: "memory");
.LBB0_333:
	v_lshl_add_u32 v140, s57, 8, v145
	v_ashrrev_i32_e32 v141, 31, v140
	v_lshl_add_u64 v[142:143], v[140:141], 2, s[18:19]
	global_load_dword v160, v[142:143], off
	global_load_dword v161, v[142:143], off offset:64
	global_load_dword v162, v[142:143], off offset:128
	global_load_dword v163, v[142:143], off offset:192
	global_load_dword v164, v[142:143], off offset:512
	global_load_dword v165, v[142:143], off offset:576
	global_load_dword v166, v[142:143], off offset:640
	global_load_dword v167, v[142:143], off offset:704
	v_max_f32_e32 v120, v120, v120
	v_max_f32_e32 v121, v121, v121
	v_max_f32_e32 v148, v116, v116
	v_max_f32_e32 v149, v117, v117
	v_max_f32_e32 v116, 0, v120
	v_max_f32_e32 v117, 0, v121
	v_max_f32_e32 v120, 0, v148
	v_max_f32_e32 v121, 0, v149
	v_lshlrev_b64 v[148:149], 13, v[140:141]
	v_max_f32_e32 v122, v122, v122
	v_max_f32_e32 v151, v118, v118
	v_max_f32_e32 v118, 0, v122
	v_max_f32_e32 v122, 0, v151
	v_max_f32_e32 v124, v124, v124
	v_max_f32_e32 v153, v112, v112
	v_max_f32_e32 v123, v123, v123
	v_max_f32_e32 v152, v119, v119
	v_max_f32_e32 v112, 0, v124
	v_max_f32_e32 v124, 0, v153
	v_max_f32_e32 v119, 0, v123
	v_max_f32_e32 v123, 0, v152
	v_max_f32_e32 v125, v125, v125
	v_max_f32_e32 v154, v113, v113
	v_max_f32_e32 v113, 0, v125
	v_max_f32_e32 v125, 0, v154
	s_lshl_b32 s26, s58, 8
	v_max_f32_e32 v126, v126, v126
	v_max_f32_e32 v127, v127, v127
	v_max_f32_e32 v155, v114, v114
	v_max_f32_e32 v156, v115, v115
	s_ashr_i32 s27, s26, 31
	v_max_f32_e32 v114, 0, v126
	v_max_f32_e32 v115, 0, v127
	v_max_f32_e32 v126, 0, v155
	v_max_f32_e32 v127, 0, v156
	s_lshl_b64 s[26:27], s[26:27], 1
	v_pk_mul_f32 v[112:113], v[112:113], v[112:113]
	v_pk_mul_f32 v[114:115], v[114:115], v[114:115]
	v_pk_mul_f32 v[116:117], v[116:117], v[116:117]
	v_pk_mul_f32 v[118:119], v[118:119], v[118:119]
	v_lshl_add_u64 v[148:149], s[10:11], 0, v[148:149]
	v_pk_mul_f32 v[120:121], v[120:121], v[120:121]
	v_pk_mul_f32 v[122:123], v[122:123], v[122:123]
	v_pk_mul_f32 v[124:125], v[124:125], v[124:125]
	v_pk_mul_f32 v[126:127], v[126:127], v[126:127]
	v_lshl_add_u64 v[148:149], v[148:149], 0, s[26:27]
	v_lshl_add_u64 v[148:149], v[148:149], 0, v[184:185]
	v_max_f32_e32 v109, v109, v109
	v_max_f32_e32 v110, v110, v110
	v_max_f32_e32 v111, v111, v111
	v_max_f32_e32 v104, v104, v104
	v_max_f32_e32 v106, v106, v106
	v_max_f32_e32 v97, v97, v97
	v_max_f32_e32 v108, v108, v108
	v_max_f32_e32 v105, v105, v105
	v_max_f32_e32 v107, v107, v107
	v_max_f32_e32 v93, v93, v93
	v_max_f32_e32 v94, v94, v94
	v_max_f32_e32 v95, v95, v95
	v_max_f32_e32 v88, v88, v88
	v_max_f32_e32 v90, v90, v90
	v_max_f32_e32 v81, v81, v81
	v_max_f32_e32 v92, v92, v92
	v_max_f32_e32 v89, v89, v89
	v_max_f32_e32 v91, v91, v91
	v_max_f32_e32 v77, v77, v77
	v_max_f32_e32 v78, v78, v78
	v_max_f32_e32 v79, v79, v79
	v_max_f32_e32 v72, v72, v72
	v_max_f32_e32 v74, v74, v74
	v_max_f32_e32 v65, v65, v65
	v_max_f32_e32 v76, v76, v76
	v_max_f32_e32 v73, v73, v73
	v_max_f32_e32 v75, v75, v75
	v_max_f32_e32 v61, v61, v61
	v_max_f32_e32 v62, v62, v62
	v_max_f32_e32 v63, v63, v63
	v_max_f32_e32 v56, v56, v56
	v_max_f32_e32 v58, v58, v58
	s_waitcnt vmcnt(7)
	v_fmamk_f32 v141, v160, 0x3a800000, v205
	v_max_f32_e32 v49, v49, v49
	v_rcp_f32_e32 v150, v141
	s_nop 0
	v_pk_mul_f32 v[114:115], v[114:115], v[150:151] op_sel_hi:[1,0]
	v_pk_mul_f32 v[112:113], v[112:113], v[150:151] op_sel_hi:[1,0]
	v_pk_mul_f32 v[118:119], v[118:119], v[150:151] op_sel_hi:[1,0]
	v_pk_mul_f32 v[116:117], v[116:117], v[150:151] op_sel_hi:[1,0]
	v_pk_mul_f32 v[122:123], v[122:123], v[150:151] op_sel_hi:[1,0]
	v_pk_mul_f32 v[120:121], v[120:121], v[150:151] op_sel_hi:[1,0]
	v_pk_mul_f32 v[126:127], v[126:127], v[150:151] op_sel_hi:[1,0]
	v_pk_mul_f32 v[124:125], v[124:125], v[150:151] op_sel_hi:[1,0]
	v_cvt_pk_bf16_f32 v112, v112, v113
	v_cvt_pk_bf16_f32 v113, v114, v115
	v_cvt_pk_bf16_f32 v114, v116, v117
	v_cvt_pk_bf16_f32 v115, v118, v119
	v_cvt_pk_bf16_f32 v116, v120, v121
	v_cvt_pk_bf16_f32 v117, v122, v123
	v_cvt_pk_bf16_f32 v118, v124, v125
	v_cvt_pk_bf16_f32 v119, v126, v127
	global_store_dwordx4 v[148:149], v[112:115], off
	global_store_dwordx4 v[148:149], v[116:119], off offset:256
	s_nop 1
	v_max_f32_e32 v112, v100, v100
	v_max_f32_e32 v116, v103, v103
	v_max_f32_e32 v117, v96, v96
	v_max_f32_e32 v119, v99, v99
	v_max_f32_e32 v99, 0, v109
	v_max_f32_e32 v109, 0, v116
	v_max_f32_e32 v118, v98, v98
	v_or_b32_e32 v96, 16, v140
	v_max_f32_e32 v100, 0, v110
	v_max_f32_e32 v110, 0, v117
	v_max_f32_e32 v113, v101, v101
	v_max_f32_e32 v115, v102, v102
	v_max_f32_e32 v101, 0, v111
	v_max_f32_e32 v102, 0, v104
	v_max_f32_e32 v104, 0, v106
	v_max_f32_e32 v106, 0, v112
	v_max_f32_e32 v111, 0, v97
	v_max_f32_e32 v112, 0, v118
	v_ashrrev_i32_e32 v97, 31, v96
	v_lshlrev_b64 v[96:97], 13, v[96:97]
	v_lshl_add_u64 v[96:97], s[10:11], 0, v[96:97]
	v_lshl_add_u64 v[96:97], v[96:97], 0, s[26:27]
	v_max_f32_e32 v98, 0, v108
	v_max_f32_e32 v108, 0, v115
	v_max_f32_e32 v103, 0, v105
	v_max_f32_e32 v105, 0, v107
	v_max_f32_e32 v107, 0, v113
	v_max_f32_e32 v113, 0, v119
	v_pk_mul_f32 v[98:99], v[98:99], v[98:99]
	v_pk_mul_f32 v[100:101], v[100:101], v[100:101]
	v_pk_mul_f32 v[102:103], v[102:103], v[102:103]
	v_pk_mul_f32 v[104:105], v[104:105], v[104:105]
	v_pk_mul_f32 v[106:107], v[106:107], v[106:107]
	v_pk_mul_f32 v[108:109], v[108:109], v[108:109]
	v_pk_mul_f32 v[110:111], v[110:111], v[110:111]
	v_pk_mul_f32 v[112:113], v[112:113], v[112:113]
	v_max_f32_e32 v60, v60, v60
	v_max_f32_e32 v57, v57, v57
	v_max_f32_e32 v59, v59, v59
	v_max_f32_e32 v45, v45, v45
	v_max_f32_e32 v46, v46, v46
	v_max_f32_e32 v47, v47, v47
	v_max_f32_e32 v40, v40, v40
	v_max_f32_e32 v42, v42, v42
	v_max_f32_e32 v33, v33, v33
	v_max_f32_e32 v44, v44, v44
	v_max_f32_e32 v41, v41, v41
	v_max_f32_e32 v43, v43, v43
	v_max_f32_e32 v29, v29, v29
	v_max_f32_e32 v30, v30, v30
	v_max_f32_e32 v31, v31, v31
	v_max_f32_e32 v24, v24, v24
	v_max_f32_e32 v26, v26, v26
	v_max_f32_e32 v17, v17, v17
	v_max_f32_e32 v28, v28, v28
	v_max_f32_e32 v25, v25, v25
	v_max_f32_e32 v27, v27, v27
	v_max_f32_e32 v15, v15, v15
	v_max_f32_e32 v1, v1, v1
	v_max_f32_e32 v13, v13, v13
	v_max_f32_e32 v14, v14, v14
	v_max_f32_e32 v8, v8, v8
	v_max_f32_e32 v10, v10, v10
	v_max_f32_e32 v12, v12, v12
	v_max_f32_e32 v9, v9, v9
	v_max_f32_e32 v11, v11, v11
	s_waitcnt vmcnt(8)
; __device__ __forceinline__ void st_bf8(bf16* p, f32x4 a, f32x4 b) { u32x4 w; w.x = pk2(a[0], a[1]); w.y = pk2(a[2], a[3]); w.z = pk2(b[0], b[1]); w.w = pk2(b[2], b[3]); *(u32x4*)p = w; }
;     __device__ __forceinline__ void operator()(AccRef acc, const pg8::Unit& u, int wr, int wc, int fr, int fq) const {
;         const int c0 = u.pn * 256;
; #pragma unroll
;         for (int ai = 0; ai < 2; ++ai)
; #pragma unroll
;             for (int m = 0; m < 4; ++m) {
;                 const int row = u.pm * 256 + ai * 128 + wr * 64 + m * 16 + fr; const size_t rw = (size_t)row;
;                 const float rs2 = 1.0f / (SSQ[row] * (1.f / 1024.f) + EPSN);
; #pragma unroll
;                 for (int bj = 0; bj < 2; ++bj) {
;                     const int cl = bj * 128 + wc * 32 + 8 * fq; const f32x4 v0 = acc[ai][bj][m][0], v1 = acc[ai][bj][m][1];
;                     f32x4 r0, r1; r0[0] = fmaxf(v0[0], 0.f); r0[1] = fmaxf(v0[1], 0.f); r0[2] = fmaxf(v0[2], 0.f); r0[3] = fmaxf(v0[3], 0.f); r1[0] = fmaxf(v1[0], 0.f); r1[1] = fmaxf(v1[1], 0.f); r1[2] = fmaxf(v1[2], 0.f); r1[3] = fmaxf(v1[3], 0.f);
;                     st_bf8(U + rw * 4096 + c0 + cl, r0 * r0 * rs2, r1 * r1 * rs2);
;                 }
;                 asm volatile("" ::: "memory");
	v_fmamk_f32 v116, v161, 0x3a800000, v205
	v_lshl_add_u64 v[114:115], v[96:97], 0, v[184:185]
	v_rcp_f32_e32 v96, v116
	s_nop 0
	v_pk_mul_f32 v[100:101], v[100:101], v[96:97] op_sel_hi:[1,0]
	v_pk_mul_f32 v[98:99], v[98:99], v[96:97] op_sel_hi:[1,0]
	v_pk_mul_f32 v[104:105], v[104:105], v[96:97] op_sel_hi:[1,0]
	v_pk_mul_f32 v[102:103], v[102:103], v[96:97] op_sel_hi:[1,0]
	v_pk_mul_f32 v[108:109], v[108:109], v[96:97] op_sel_hi:[1,0]
	v_pk_mul_f32 v[106:107], v[106:107], v[96:97] op_sel_hi:[1,0]
	v_pk_mul_f32 v[112:113], v[112:113], v[96:97] op_sel_hi:[1,0]
	v_pk_mul_f32 v[110:111], v[110:111], v[96:97] op_sel_hi:[1,0]
	v_cvt_pk_bf16_f32 v96, v98, v99
	v_cvt_pk_bf16_f32 v97, v100, v101
	v_cvt_pk_bf16_f32 v98, v102, v103
	v_cvt_pk_bf16_f32 v99, v104, v105
	v_cvt_pk_bf16_f32 v100, v106, v107
	v_cvt_pk_bf16_f32 v101, v108, v109
	v_cvt_pk_bf16_f32 v102, v110, v111
	v_cvt_pk_bf16_f32 v103, v112, v113
	global_store_dwordx4 v[114:115], v[96:99], off
	global_store_dwordx4 v[114:115], v[100:103], off offset:256
	s_nop 1
	v_max_f32_e32 v96, v84, v84
	v_max_f32_e32 v100, v87, v87
	v_max_f32_e32 v101, v80, v80
	v_max_f32_e32 v103, v83, v83
	v_max_f32_e32 v83, 0, v93
	v_max_f32_e32 v93, 0, v100
	v_max_f32_e32 v102, v82, v82
	v_or_b32_e32 v80, 32, v140
	v_max_f32_e32 v84, 0, v94
	v_max_f32_e32 v94, 0, v101
	v_max_f32_e32 v97, v85, v85
	v_max_f32_e32 v99, v86, v86
	v_max_f32_e32 v85, 0, v95
	v_max_f32_e32 v86, 0, v88
	v_max_f32_e32 v88, 0, v90
	v_max_f32_e32 v90, 0, v96
	v_max_f32_e32 v95, 0, v81
	v_max_f32_e32 v96, 0, v102
	v_ashrrev_i32_e32 v81, 31, v80
	v_lshlrev_b64 v[80:81], 13, v[80:81]
	v_lshl_add_u64 v[80:81], s[10:11], 0, v[80:81]
	v_lshl_add_u64 v[80:81], v[80:81], 0, s[26:27]
	v_max_f32_e32 v82, 0, v92
	v_max_f32_e32 v92, 0, v99
	v_max_f32_e32 v87, 0, v89
	v_max_f32_e32 v89, 0, v91
	v_max_f32_e32 v91, 0, v97
	v_max_f32_e32 v97, 0, v103
	v_pk_mul_f32 v[82:83], v[82:83], v[82:83]
	v_pk_mul_f32 v[84:85], v[84:85], v[84:85]
	v_pk_mul_f32 v[86:87], v[86:87], v[86:87]
	v_pk_mul_f32 v[88:89], v[88:89], v[88:89]
	v_pk_mul_f32 v[90:91], v[90:91], v[90:91]
	v_pk_mul_f32 v[92:93], v[92:93], v[92:93]
	v_pk_mul_f32 v[94:95], v[94:95], v[94:95]
	v_pk_mul_f32 v[96:97], v[96:97], v[96:97]
	s_waitcnt vmcnt(9)
	v_fmamk_f32 v100, v162, 0x3a800000, v205
	v_lshl_add_u64 v[98:99], v[80:81], 0, v[184:185]
	v_rcp_f32_e32 v80, v100
	s_nop 0
	v_pk_mul_f32 v[84:85], v[84:85], v[80:81] op_sel_hi:[1,0]
	v_pk_mul_f32 v[82:83], v[82:83], v[80:81] op_sel_hi:[1,0]
	v_pk_mul_f32 v[88:89], v[88:89], v[80:81] op_sel_hi:[1,0]
	v_pk_mul_f32 v[86:87], v[86:87], v[80:81] op_sel_hi:[1,0]
	v_pk_mul_f32 v[92:93], v[92:93], v[80:81] op_sel_hi:[1,0]
	v_pk_mul_f32 v[90:91], v[90:91], v[80:81] op_sel_hi:[1,0]
	v_pk_mul_f32 v[96:97], v[96:97], v[80:81] op_sel_hi:[1,0]
	v_pk_mul_f32 v[94:95], v[94:95], v[80:81] op_sel_hi:[1,0]
	v_cvt_pk_bf16_f32 v80, v82, v83
	v_cvt_pk_bf16_f32 v81, v84, v85
	v_cvt_pk_bf16_f32 v82, v86, v87
	v_cvt_pk_bf16_f32 v83, v88, v89
	v_cvt_pk_bf16_f32 v84, v90, v91
	v_cvt_pk_bf16_f32 v85, v92, v93
	v_cvt_pk_bf16_f32 v86, v94, v95
	v_cvt_pk_bf16_f32 v87, v96, v97
	global_store_dwordx4 v[98:99], v[80:83], off
	global_store_dwordx4 v[98:99], v[84:87], off offset:256
	s_nop 1
	v_max_f32_e32 v80, v68, v68
	v_max_f32_e32 v84, v71, v71
	v_max_f32_e32 v85, v64, v64
	v_max_f32_e32 v87, v67, v67
	v_max_f32_e32 v67, 0, v77
	v_max_f32_e32 v77, 0, v84
	v_max_f32_e32 v86, v66, v66
	v_or_b32_e32 v64, 48, v140
	v_max_f32_e32 v68, 0, v78
	v_max_f32_e32 v78, 0, v85
	v_max_f32_e32 v81, v69, v69
	v_max_f32_e32 v83, v70, v70
	v_max_f32_e32 v69, 0, v79
	v_max_f32_e32 v70, 0, v72
	v_max_f32_e32 v72, 0, v74
	v_max_f32_e32 v74, 0, v80
	v_max_f32_e32 v79, 0, v65
	v_max_f32_e32 v80, 0, v86
	v_ashrrev_i32_e32 v65, 31, v64
	v_lshlrev_b64 v[64:65], 13, v[64:65]
	v_lshl_add_u64 v[64:65], s[10:11], 0, v[64:65]
	v_lshl_add_u64 v[64:65], v[64:65], 0, s[26:27]
	v_max_f32_e32 v66, 0, v76
	v_max_f32_e32 v76, 0, v83
	v_max_f32_e32 v71, 0, v73
	v_max_f32_e32 v73, 0, v75
	v_max_f32_e32 v75, 0, v81
	v_max_f32_e32 v81, 0, v87
	v_pk_mul_f32 v[66:67], v[66:67], v[66:67]
	v_pk_mul_f32 v[68:69], v[68:69], v[68:69]
	v_pk_mul_f32 v[70:71], v[70:71], v[70:71]
	v_pk_mul_f32 v[72:73], v[72:73], v[72:73]
	v_pk_mul_f32 v[74:75], v[74:75], v[74:75]
	v_pk_mul_f32 v[76:77], v[76:77], v[76:77]
	v_pk_mul_f32 v[78:79], v[78:79], v[78:79]
	v_pk_mul_f32 v[80:81], v[80:81], v[80:81]
	s_waitcnt vmcnt(10)
	v_fmamk_f32 v84, v163, 0x3a800000, v205
	v_lshl_add_u64 v[82:83], v[64:65], 0, v[184:185]
	v_rcp_f32_e32 v64, v84
	s_nop 0
	v_pk_mul_f32 v[68:69], v[68:69], v[64:65] op_sel_hi:[1,0]
	v_pk_mul_f32 v[66:67], v[66:67], v[64:65] op_sel_hi:[1,0]
	v_pk_mul_f32 v[72:73], v[72:73], v[64:65] op_sel_hi:[1,0]
	v_pk_mul_f32 v[70:71], v[70:71], v[64:65] op_sel_hi:[1,0]
	v_pk_mul_f32 v[76:77], v[76:77], v[64:65] op_sel_hi:[1,0]
	v_pk_mul_f32 v[74:75], v[74:75], v[64:65] op_sel_hi:[1,0]
	v_pk_mul_f32 v[80:81], v[80:81], v[64:65] op_sel_hi:[1,0]
	v_pk_mul_f32 v[78:79], v[78:79], v[64:65] op_sel_hi:[1,0]
	v_cvt_pk_bf16_f32 v64, v66, v67
	v_cvt_pk_bf16_f32 v65, v68, v69
	v_cvt_pk_bf16_f32 v66, v70, v71
	v_cvt_pk_bf16_f32 v67, v72, v73
	v_cvt_pk_bf16_f32 v68, v74, v75
	v_cvt_pk_bf16_f32 v69, v76, v77
	v_cvt_pk_bf16_f32 v70, v78, v79
	v_cvt_pk_bf16_f32 v71, v80, v81
	global_store_dwordx4 v[82:83], v[64:67], off
	global_store_dwordx4 v[82:83], v[68:71], off offset:256
	s_nop 1
	v_max_f32_e32 v64, v52, v52
	v_max_f32_e32 v68, v55, v55
	v_max_f32_e32 v69, v48, v48
	v_max_f32_e32 v71, v51, v51
	v_max_f32_e32 v51, 0, v61
	v_max_f32_e32 v61, 0, v68
	v_max_f32_e32 v70, v50, v50
	v_add_u32_e32 v48, 0x80, v140
	v_max_f32_e32 v52, 0, v62
	v_max_f32_e32 v62, 0, v69
	v_max_f32_e32 v65, v53, v53
	v_max_f32_e32 v67, v54, v54
	v_max_f32_e32 v53, 0, v63
	v_max_f32_e32 v54, 0, v56
	v_max_f32_e32 v56, 0, v58
	v_max_f32_e32 v58, 0, v64
	v_max_f32_e32 v63, 0, v49
	v_max_f32_e32 v64, 0, v70
	v_ashrrev_i32_e32 v49, 31, v48
	v_lshlrev_b64 v[48:49], 13, v[48:49]
	v_lshl_add_u64 v[48:49], s[10:11], 0, v[48:49]
	v_lshl_add_u64 v[48:49], v[48:49], 0, s[26:27]
	v_max_f32_e32 v50, 0, v60
	v_max_f32_e32 v60, 0, v67
	v_max_f32_e32 v55, 0, v57
	v_max_f32_e32 v57, 0, v59
	v_max_f32_e32 v59, 0, v65
	v_max_f32_e32 v65, 0, v71
	v_pk_mul_f32 v[50:51], v[50:51], v[50:51]
	v_pk_mul_f32 v[52:53], v[52:53], v[52:53]
	v_pk_mul_f32 v[54:55], v[54:55], v[54:55]
	v_pk_mul_f32 v[56:57], v[56:57], v[56:57]
	v_pk_mul_f32 v[58:59], v[58:59], v[58:59]
	v_pk_mul_f32 v[60:61], v[60:61], v[60:61]
	v_pk_mul_f32 v[62:63], v[62:63], v[62:63]
	v_pk_mul_f32 v[64:65], v[64:65], v[64:65]
	s_waitcnt vmcnt(11)
; __device__ __forceinline__ void st_bf8(bf16* p, f32x4 a, f32x4 b) { u32x4 w; w.x = pk2(a[0], a[1]); w.y = pk2(a[2], a[3]); w.z = pk2(b[0], b[1]); w.w = pk2(b[2], b[3]); *(u32x4*)p = w; }
;     __device__ __forceinline__ void operator()(AccRef acc, const pg8::Unit& u, int wr, int wc, int fr, int fq) const {
;         const int c0 = u.pn * 256;
; #pragma unroll
;         for (int ai = 0; ai < 2; ++ai)
; #pragma unroll
;             for (int m = 0; m < 4; ++m) {
;                 const int row = u.pm * 256 + ai * 128 + wr * 64 + m * 16 + fr; const size_t rw = (size_t)row;
;                 const float rs2 = 1.0f / (SSQ[row] * (1.f / 1024.f) + EPSN);
; #pragma unroll
;                 for (int bj = 0; bj < 2; ++bj) {
;                     const int cl = bj * 128 + wc * 32 + 8 * fq; const f32x4 v0 = acc[ai][bj][m][0], v1 = acc[ai][bj][m][1];
;                     f32x4 r0, r1; r0[0] = fmaxf(v0[0], 0.f); r0[1] = fmaxf(v0[1], 0.f); r0[2] = fmaxf(v0[2], 0.f); r0[3] = fmaxf(v0[3], 0.f); r1[0] = fmaxf(v1[0], 0.f); r1[1] = fmaxf(v1[1], 0.f); r1[2] = fmaxf(v1[2], 0.f); r1[3] = fmaxf(v1[3], 0.f);
;                     st_bf8(U + rw * 4096 + c0 + cl, r0 * r0 * rs2, r1 * r1 * rs2);
;                 }
;                 asm volatile("" ::: "memory");
	v_fmamk_f32 v68, v164, 0x3a800000, v205
	v_lshl_add_u64 v[66:67], v[48:49], 0, v[184:185]
	v_rcp_f32_e32 v48, v68
	s_nop 0
	v_pk_mul_f32 v[52:53], v[52:53], v[48:49] op_sel_hi:[1,0]
	v_pk_mul_f32 v[50:51], v[50:51], v[48:49] op_sel_hi:[1,0]
	v_pk_mul_f32 v[56:57], v[56:57], v[48:49] op_sel_hi:[1,0]
	v_pk_mul_f32 v[54:55], v[54:55], v[48:49] op_sel_hi:[1,0]
	v_pk_mul_f32 v[60:61], v[60:61], v[48:49] op_sel_hi:[1,0]
	v_pk_mul_f32 v[58:59], v[58:59], v[48:49] op_sel_hi:[1,0]
	v_pk_mul_f32 v[64:65], v[64:65], v[48:49] op_sel_hi:[1,0]
	v_pk_mul_f32 v[62:63], v[62:63], v[48:49] op_sel_hi:[1,0]
	v_cvt_pk_bf16_f32 v48, v50, v51
	v_cvt_pk_bf16_f32 v49, v52, v53
	v_cvt_pk_bf16_f32 v50, v54, v55
	v_cvt_pk_bf16_f32 v51, v56, v57
	v_cvt_pk_bf16_f32 v52, v58, v59
	v_cvt_pk_bf16_f32 v53, v60, v61
	v_cvt_pk_bf16_f32 v54, v62, v63
	v_cvt_pk_bf16_f32 v55, v64, v65
	global_store_dwordx4 v[66:67], v[48:51], off
	global_store_dwordx4 v[66:67], v[52:55], off offset:256
	s_nop 1
	v_max_f32_e32 v48, v36, v36
	v_max_f32_e32 v52, v39, v39
	v_max_f32_e32 v53, v32, v32
	v_max_f32_e32 v55, v35, v35
	v_max_f32_e32 v35, 0, v45
	v_max_f32_e32 v45, 0, v52
	v_max_f32_e32 v54, v34, v34
	v_add_u32_e32 v32, 0x90, v140
	v_max_f32_e32 v36, 0, v46
	v_max_f32_e32 v46, 0, v53
	v_max_f32_e32 v49, v37, v37
	v_max_f32_e32 v51, v38, v38
	v_max_f32_e32 v37, 0, v47
	v_max_f32_e32 v38, 0, v40
	v_max_f32_e32 v40, 0, v42
	v_max_f32_e32 v42, 0, v48
	v_max_f32_e32 v47, 0, v33
	v_max_f32_e32 v48, 0, v54
	v_ashrrev_i32_e32 v33, 31, v32
	v_lshlrev_b64 v[32:33], 13, v[32:33]
	v_lshl_add_u64 v[32:33], s[10:11], 0, v[32:33]
	v_lshl_add_u64 v[32:33], v[32:33], 0, s[26:27]
	v_max_f32_e32 v34, 0, v44
	v_max_f32_e32 v44, 0, v51
	v_max_f32_e32 v39, 0, v41
	v_max_f32_e32 v41, 0, v43
	v_max_f32_e32 v43, 0, v49
	v_max_f32_e32 v49, 0, v55
	v_pk_mul_f32 v[34:35], v[34:35], v[34:35]
	v_pk_mul_f32 v[36:37], v[36:37], v[36:37]
	v_pk_mul_f32 v[38:39], v[38:39], v[38:39]
	v_pk_mul_f32 v[40:41], v[40:41], v[40:41]
	v_pk_mul_f32 v[42:43], v[42:43], v[42:43]
	v_pk_mul_f32 v[44:45], v[44:45], v[44:45]
	v_pk_mul_f32 v[46:47], v[46:47], v[46:47]
	v_pk_mul_f32 v[48:49], v[48:49], v[48:49]
	s_waitcnt vmcnt(12)
	v_fmamk_f32 v52, v165, 0x3a800000, v205
	v_lshl_add_u64 v[50:51], v[32:33], 0, v[184:185]
	v_rcp_f32_e32 v32, v52
	s_nop 0
	v_pk_mul_f32 v[36:37], v[36:37], v[32:33] op_sel_hi:[1,0]
	v_pk_mul_f32 v[34:35], v[34:35], v[32:33] op_sel_hi:[1,0]
	v_pk_mul_f32 v[40:41], v[40:41], v[32:33] op_sel_hi:[1,0]
	v_pk_mul_f32 v[38:39], v[38:39], v[32:33] op_sel_hi:[1,0]
	v_pk_mul_f32 v[44:45], v[44:45], v[32:33] op_sel_hi:[1,0]
	v_pk_mul_f32 v[42:43], v[42:43], v[32:33] op_sel_hi:[1,0]
	v_pk_mul_f32 v[48:49], v[48:49], v[32:33] op_sel_hi:[1,0]
	v_pk_mul_f32 v[46:47], v[46:47], v[32:33] op_sel_hi:[1,0]
	v_cvt_pk_bf16_f32 v32, v34, v35
	v_cvt_pk_bf16_f32 v33, v36, v37
	v_cvt_pk_bf16_f32 v34, v38, v39
	v_cvt_pk_bf16_f32 v35, v40, v41
	v_cvt_pk_bf16_f32 v36, v42, v43
	v_cvt_pk_bf16_f32 v37, v44, v45
	v_cvt_pk_bf16_f32 v38, v46, v47
	v_cvt_pk_bf16_f32 v39, v48, v49
	global_store_dwordx4 v[50:51], v[32:35], off
	global_store_dwordx4 v[50:51], v[36:39], off offset:256
	s_nop 1
	v_max_f32_e32 v32, v20, v20
	v_max_f32_e32 v36, v23, v23
	v_max_f32_e32 v37, v16, v16
	v_max_f32_e32 v39, v19, v19
	v_max_f32_e32 v19, 0, v29
	v_max_f32_e32 v29, 0, v36
	v_max_f32_e32 v38, v18, v18
	v_add_u32_e32 v16, 0xa0, v140
	v_max_f32_e32 v20, 0, v30
	v_max_f32_e32 v30, 0, v37
	v_max_f32_e32 v33, v21, v21
	v_max_f32_e32 v35, v22, v22
	v_max_f32_e32 v21, 0, v31
	v_max_f32_e32 v22, 0, v24
	v_max_f32_e32 v24, 0, v26
	v_max_f32_e32 v26, 0, v32
	v_max_f32_e32 v31, 0, v17
	v_max_f32_e32 v32, 0, v38
	v_ashrrev_i32_e32 v17, 31, v16
	v_lshlrev_b64 v[16:17], 13, v[16:17]
	v_lshl_add_u64 v[16:17], s[10:11], 0, v[16:17]
	v_lshl_add_u64 v[16:17], v[16:17], 0, s[26:27]
	v_max_f32_e32 v18, 0, v28
	v_max_f32_e32 v28, 0, v35
	v_max_f32_e32 v23, 0, v25
	v_max_f32_e32 v25, 0, v27
	v_max_f32_e32 v27, 0, v33
	v_max_f32_e32 v33, 0, v39
	v_pk_mul_f32 v[18:19], v[18:19], v[18:19]
	v_pk_mul_f32 v[20:21], v[20:21], v[20:21]
	v_pk_mul_f32 v[22:23], v[22:23], v[22:23]
	v_pk_mul_f32 v[24:25], v[24:25], v[24:25]
	v_pk_mul_f32 v[26:27], v[26:27], v[26:27]
	v_pk_mul_f32 v[28:29], v[28:29], v[28:29]
	v_pk_mul_f32 v[30:31], v[30:31], v[30:31]
	v_pk_mul_f32 v[32:33], v[32:33], v[32:33]
	s_waitcnt vmcnt(13)
; __device__ __forceinline__ void st_bf8(bf16* p, f32x4 a, f32x4 b) { u32x4 w; w.x = pk2(a[0], a[1]); w.y = pk2(a[2], a[3]); w.z = pk2(b[0], b[1]); w.w = pk2(b[2], b[3]); *(u32x4*)p = w; }
;     __device__ __forceinline__ void operator()(AccRef acc, const pg8::Unit& u, int wr, int wc, int fr, int fq) const {
;         const int c0 = u.pn * 256;
; #pragma unroll
;         for (int ai = 0; ai < 2; ++ai)
; #pragma unroll
;             for (int m = 0; m < 4; ++m) {
;                 const int row = u.pm * 256 + ai * 128 + wr * 64 + m * 16 + fr; const size_t rw = (size_t)row;
;                 const float rs2 = 1.0f / (SSQ[row] * (1.f / 1024.f) + EPSN);
; #pragma unroll
;                 for (int bj = 0; bj < 2; ++bj) {
;                     const int cl = bj * 128 + wc * 32 + 8 * fq; const f32x4 v0 = acc[ai][bj][m][0], v1 = acc[ai][bj][m][1];
;                     f32x4 r0, r1; r0[0] = fmaxf(v0[0], 0.f); r0[1] = fmaxf(v0[1], 0.f); r0[2] = fmaxf(v0[2], 0.f); r0[3] = fmaxf(v0[3], 0.f); r1[0] = fmaxf(v1[0], 0.f); r1[1] = fmaxf(v1[1], 0.f); r1[2] = fmaxf(v1[2], 0.f); r1[3] = fmaxf(v1[3], 0.f);
;                     st_bf8(U + rw * 4096 + c0 + cl, r0 * r0 * rs2, r1 * r1 * rs2);
;                 }
;                 asm volatile("" ::: "memory");
;             }
;     }
	v_fmamk_f32 v36, v166, 0x3a800000, v205
	v_lshl_add_u64 v[34:35], v[16:17], 0, v[184:185]
	v_rcp_f32_e32 v16, v36
	s_nop 0
	v_pk_mul_f32 v[20:21], v[20:21], v[16:17] op_sel_hi:[1,0]
	v_pk_mul_f32 v[18:19], v[18:19], v[16:17] op_sel_hi:[1,0]
	v_pk_mul_f32 v[24:25], v[24:25], v[16:17] op_sel_hi:[1,0]
	v_pk_mul_f32 v[22:23], v[22:23], v[16:17] op_sel_hi:[1,0]
	v_pk_mul_f32 v[28:29], v[28:29], v[16:17] op_sel_hi:[1,0]
	v_pk_mul_f32 v[26:27], v[26:27], v[16:17] op_sel_hi:[1,0]
	v_pk_mul_f32 v[32:33], v[32:33], v[16:17] op_sel_hi:[1,0]
	v_pk_mul_f32 v[30:31], v[30:31], v[16:17] op_sel_hi:[1,0]
	v_cvt_pk_bf16_f32 v16, v18, v19
	v_cvt_pk_bf16_f32 v17, v20, v21
	v_cvt_pk_bf16_f32 v18, v22, v23
	v_cvt_pk_bf16_f32 v19, v24, v25
	v_cvt_pk_bf16_f32 v20, v26, v27
	v_cvt_pk_bf16_f32 v21, v28, v29
	v_cvt_pk_bf16_f32 v22, v30, v31
	v_cvt_pk_bf16_f32 v23, v32, v33
	global_store_dwordx4 v[34:35], v[16:19], off
	global_store_dwordx4 v[34:35], v[20:23], off offset:256
	s_nop 1
	v_max_f32_e32 v17, v5, v5
	v_max_f32_e32 v21, v0, v0
	v_add_u32_e32 v0, 0xb0, v140
	v_max_f32_e32 v5, 0, v15
	v_max_f32_e32 v15, 0, v1
	v_ashrrev_i32_e32 v1, 31, v0
	v_max_f32_e32 v20, v7, v7
	v_lshlrev_b64 v[0:1], 13, v[0:1]
	v_max_f32_e32 v23, v3, v3
	v_max_f32_e32 v3, 0, v13
	v_max_f32_e32 v13, 0, v20
	v_lshl_add_u64 v[0:1], s[10:11], 0, v[0:1]
	v_max_f32_e32 v16, v4, v4
	v_max_f32_e32 v22, v2, v2
	v_max_f32_e32 v4, 0, v14
	v_max_f32_e32 v14, 0, v21
	v_lshl_add_u64 v[0:1], v[0:1], 0, s[26:27]
	v_max_f32_e32 v19, v6, v6
	v_max_f32_e32 v6, 0, v8
	v_max_f32_e32 v8, 0, v10
	v_max_f32_e32 v10, 0, v16
	v_max_f32_e32 v16, 0, v22
	v_max_f32_e32 v2, 0, v12
	v_max_f32_e32 v12, 0, v19
	v_max_f32_e32 v7, 0, v9
	v_max_f32_e32 v9, 0, v11
	v_max_f32_e32 v11, 0, v17
	v_max_f32_e32 v17, 0, v23
	v_pk_mul_f32 v[2:3], v[2:3], v[2:3]
	v_pk_mul_f32 v[4:5], v[4:5], v[4:5]
	v_pk_mul_f32 v[6:7], v[6:7], v[6:7]
	v_pk_mul_f32 v[8:9], v[8:9], v[8:9]
	v_pk_mul_f32 v[10:11], v[10:11], v[10:11]
	v_pk_mul_f32 v[12:13], v[12:13], v[12:13]
	v_pk_mul_f32 v[14:15], v[14:15], v[14:15]
	v_pk_mul_f32 v[16:17], v[16:17], v[16:17]
	s_waitcnt vmcnt(14)
	v_fmamk_f32 v20, v167, 0x3a800000, v205
	v_lshl_add_u64 v[18:19], v[0:1], 0, v[184:185]
	v_rcp_f32_e32 v0, v20
	s_nop 0
	v_pk_mul_f32 v[4:5], v[4:5], v[0:1] op_sel_hi:[1,0]
	v_pk_mul_f32 v[2:3], v[2:3], v[0:1] op_sel_hi:[1,0]
	v_pk_mul_f32 v[8:9], v[8:9], v[0:1] op_sel_hi:[1,0]
	v_pk_mul_f32 v[6:7], v[6:7], v[0:1] op_sel_hi:[1,0]
	v_pk_mul_f32 v[12:13], v[12:13], v[0:1] op_sel_hi:[1,0]
	v_pk_mul_f32 v[10:11], v[10:11], v[0:1] op_sel_hi:[1,0]
	v_pk_mul_f32 v[16:17], v[16:17], v[0:1] op_sel_hi:[1,0]
	v_pk_mul_f32 v[14:15], v[14:15], v[0:1] op_sel_hi:[1,0]
	v_cvt_pk_bf16_f32 v0, v2, v3
	v_cvt_pk_bf16_f32 v1, v4, v5
	v_cvt_pk_bf16_f32 v2, v6, v7
	v_cvt_pk_bf16_f32 v3, v8, v9
	v_cvt_pk_bf16_f32 v4, v10, v11
	v_cvt_pk_bf16_f32 v5, v12, v13
	v_cvt_pk_bf16_f32 v6, v14, v15
	v_cvt_pk_bf16_f32 v7, v16, v17
	global_store_dwordx4 v[18:19], v[0:3], off
	global_store_dwordx4 v[18:19], v[4:7], off offset:256
	s_and_b64 vcc, exec, s[0:1]
	s_mov_b64 s[0:1], -1
	s_cbranch_vccnz .LBB0_320
	s_andn2_b64 vcc, exec, s[16:17]
	s_cbranch_vccnz .LBB0_319
	s_barrier
	s_branch .LBB0_319

; __device__ __forceinline__ unsigned f2bf(float f) { return pk2(f, 0.f) & 0xffffu; }
; __device__ __forceinline__ int crow(int r, int hi) { return (r & 3) + 8 * (r >> 2) + 4 * hi; }
; __device__ __forceinline__ float xsum32(float v) { auto rr = __builtin_amdgcn_permlane32_swap(__float_as_uint(v), __float_as_uint(v), false, false); return __uint_as_float(rr[0]) + __uint_as_float(rr[1]); }
; template <bool DIFF>
; __device__ __forceinline__ void attn_unit_coop(const Grp& G, int b, int h, int qb, int n, LAS unsigned char* lds, const int tid_in) {
;     ...
;         const float lt = xsum32(st.l);
;         if (hi == 0) wsf[32 + q] = lt;
;         float inv[16];
; #pragma unroll
;         for (int r = 0; r < 16; ++r) inv[r] = 1.0f / wsf[32 + crow(r, hi)];
;         bf16* obase = (DIFF ? (n == 0 ? G.DO : G.XN) + h * 128 : G.MO + h * 64) + (seq0 + qrow0) * 1024 + q;
; #pragma unroll
;         for (int db = 0; db < NDB; ++db)
; #pragma unroll
;             for (int r = 0; r < 16; ++r) obase[(size_t)crow(r, hi) * 1024 + db * 32] = (bf16)f2bf(st.o[db][r] * inv[r]);
.LBB0_518:
	s_or_b64 exec, exec, s[2:3]
	ds_read_b128 v[68:71], v213 offset:6272
	ds_read_b128 v[64:67], v213 offset:6304
	v_lshlrev_b32_e32 v184, 1, v194
	s_waitcnt lgkmcnt(1)
	v_rcp_f32_e32 v68, v68
	s_nop 0
	v_mul_f32_e32 v48, v48, v68
	v_mul_f32_e32 v32, v32, v68
	v_mul_f32_e32 v16, v16, v68
	v_rcp_f32_e32 v69, v69
	v_mul_f32_e32 v0, v0, v68
	v_rcp_f32_e32 v70, v70
	v_rcp_f32_e32 v71, v71
	s_waitcnt lgkmcnt(0)
	v_rcp_f32_e32 v72, v64
	s_nop 0
	v_mul_f32_e32 v52, v52, v72
	v_rcp_f32_e32 v73, v65
	v_rcp_f32_e32 v74, v66
	s_nop 0
	v_mul_f32_e32 v54, v54, v74
	v_rcp_f32_e32 v75, v67
	ds_read_b128 v[64:67], v213 offset:6336
	s_waitcnt lgkmcnt(0)
	v_rcp_f32_e32 v76, v64
	s_nop 0
	v_mul_f32_e32 v56, v56, v76
	v_rcp_f32_e32 v77, v65
	v_rcp_f32_e32 v78, v66
	s_nop 0
	v_mul_f32_e32 v58, v58, v78
	v_rcp_f32_e32 v79, v67
	ds_read_b128 v[64:67], v213 offset:6368
	s_waitcnt lgkmcnt(0)
	v_rcp_f32_e32 v94, v64
	s_nop 0
	v_mul_f32_e32 v60, v60, v94
	v_rcp_f32_e32 v95, v65
	v_rcp_f32_e32 v96, v66
	s_lshl_b64 s[0:1], s[38:39], 11
	s_add_u32 s0, s80, s0
	s_addc_u32 s1, s81, s1
	v_rcp_f32_e32 v97, v67
	v_lshl_add_u64 v[64:65], s[0:1], 0, v[184:185]
	v_lshlrev_b32_e32 v184, 13, v191
	v_cvt_pk_bf16_f32 v48, v48, s0
	v_lshl_add_u64 v[66:67], v[64:65], 0, v[184:185]
	global_store_short v[66:67], v48, off
	v_mul_f32_e32 v48, v49, v69
	v_cvt_pk_bf16_f32 v48, v48, s0
	global_store_short v[66:67], v48, off offset:2048
	v_mul_f32_e32 v48, v50, v70
	v_cvt_pk_bf16_f32 v50, v48, s0
	v_or_b32_e32 v48, 0x1000, v184
	v_mov_b32_e32 v49, v185
	v_lshl_add_u64 v[80:81], v[64:65], 0, v[48:49]
	global_store_short v[80:81], v50, off
	v_mul_f32_e32 v50, v51, v71
	v_cvt_pk_bf16_f32 v82, v50, s0
	v_or_b32_e32 v50, 0x1800, v184
	v_mov_b32_e32 v51, v185
	v_lshl_add_u64 v[80:81], v[64:65], 0, v[50:51]
	global_store_short v[80:81], v82, off
	v_or_b32_e32 v80, 0x4000, v184
	v_mov_b32_e32 v81, v185
	v_cvt_pk_bf16_f32 v52, v52, s0
	v_lshl_add_u64 v[82:83], v[64:65], 0, v[80:81]
	global_store_short v[82:83], v52, off
	v_mul_f32_e32 v52, v53, v73
	v_cvt_pk_bf16_f32 v84, v52, s0
	v_or_b32_e32 v52, 0x4800, v184
	v_mov_b32_e32 v53, v185
	v_lshl_add_u64 v[82:83], v[64:65], 0, v[52:53]
	global_store_short v[82:83], v84, off
	v_or_b32_e32 v82, 0x5000, v184
	v_mov_b32_e32 v83, v185
	v_cvt_pk_bf16_f32 v54, v54, s0
	v_lshl_add_u64 v[84:85], v[64:65], 0, v[82:83]
	global_store_short v[84:85], v54, off
	v_mul_f32_e32 v54, v55, v75
	v_cvt_pk_bf16_f32 v86, v54, s0
	v_or_b32_e32 v54, 0x5800, v184
	v_mov_b32_e32 v55, v185
	v_lshl_add_u64 v[84:85], v[64:65], 0, v[54:55]
	global_store_short v[84:85], v86, off
	v_or_b32_e32 v84, 0x8000, v184
	v_mov_b32_e32 v85, v185
	v_cvt_pk_bf16_f32 v56, v56, s0
	v_lshl_add_u64 v[86:87], v[64:65], 0, v[84:85]
	global_store_short v[86:87], v56, off
	v_mul_f32_e32 v56, v57, v77
	v_cvt_pk_bf16_f32 v88, v56, s0
	v_or_b32_e32 v56, 0x8800, v184
	v_mov_b32_e32 v57, v185
	v_lshl_add_u64 v[86:87], v[64:65], 0, v[56:57]
	global_store_short v[86:87], v88, off
	v_or_b32_e32 v86, 0x9000, v184
	v_mov_b32_e32 v87, v185
	v_cvt_pk_bf16_f32 v58, v58, s0
	v_lshl_add_u64 v[88:89], v[64:65], 0, v[86:87]
	global_store_short v[88:89], v58, off
	v_mul_f32_e32 v58, v59, v79
	v_cvt_pk_bf16_f32 v90, v58, s0
	v_or_b32_e32 v58, 0x9800, v184
	v_mov_b32_e32 v59, v185
	v_lshl_add_u64 v[88:89], v[64:65], 0, v[58:59]
	global_store_short v[88:89], v90, off
	v_or_b32_e32 v88, 0xc000, v184
	v_mov_b32_e32 v89, v185
	v_cvt_pk_bf16_f32 v60, v60, s0
	v_lshl_add_u64 v[90:91], v[64:65], 0, v[88:89]
	global_store_short v[90:91], v60, off
	v_mul_f32_e32 v60, v61, v95
	v_cvt_pk_bf16_f32 v92, v60, s0
	v_or_b32_e32 v60, 0xc800, v184
	v_mov_b32_e32 v61, v185
	v_lshl_add_u64 v[90:91], v[64:65], 0, v[60:61]
	global_store_short v[90:91], v92, off
	v_mul_f32_e32 v62, v62, v96
	v_or_b32_e32 v90, 0xd000, v184
	v_mov_b32_e32 v91, v185
	v_cvt_pk_bf16_f32 v62, v62, s0
	v_lshl_add_u64 v[92:93], v[64:65], 0, v[90:91]
	v_cvt_pk_bf16_f32 v32, v32, s0
	global_store_short v[92:93], v62, off
	v_mul_f32_e32 v62, v63, v97
	v_or_b32_e32 v184, 0xd800, v184
	global_store_short v[66:67], v32, off offset:64
	v_mul_f32_e32 v32, v33, v69
	v_cvt_pk_bf16_f32 v92, v62, s0
	v_lshl_add_u64 v[62:63], v[64:65], 0, v[184:185]
	v_cvt_pk_bf16_f32 v32, v32, s0
	global_store_short v[62:63], v92, off
	v_lshl_add_u64 v[62:63], v[64:65], 0, 64
	global_store_short v[66:67], v32, off offset:2112
	v_mul_f32_e32 v32, v34, v70
	v_cvt_pk_bf16_f32 v34, v32, s0
	v_lshl_add_u64 v[32:33], v[62:63], 0, v[48:49]
	global_store_short v[32:33], v34, off
	v_mul_f32_e32 v32, v35, v71
	v_cvt_pk_bf16_f32 v34, v32, s0
	v_lshl_add_u64 v[32:33], v[62:63], 0, v[50:51]
	global_store_short v[32:33], v34, off
	v_mul_f32_e32 v32, v36, v72
	v_cvt_pk_bf16_f32 v34, v32, s0
	v_lshl_add_u64 v[32:33], v[62:63], 0, v[80:81]
	global_store_short v[32:33], v34, off
	v_mul_f32_e32 v32, v37, v73
	v_cvt_pk_bf16_f32 v34, v32, s0
	v_lshl_add_u64 v[32:33], v[62:63], 0, v[52:53]
	global_store_short v[32:33], v34, off
	v_mul_f32_e32 v32, v38, v74
	v_cvt_pk_bf16_f32 v34, v32, s0
	v_lshl_add_u64 v[32:33], v[62:63], 0, v[82:83]
	global_store_short v[32:33], v34, off
	v_mul_f32_e32 v32, v39, v75
	v_cvt_pk_bf16_f32 v34, v32, s0
	v_lshl_add_u64 v[32:33], v[62:63], 0, v[54:55]
	global_store_short v[32:33], v34, off
	v_mul_f32_e32 v32, v40, v76
	v_cvt_pk_bf16_f32 v34, v32, s0
	v_lshl_add_u64 v[32:33], v[62:63], 0, v[84:85]
	global_store_short v[32:33], v34, off
	v_mul_f32_e32 v32, v41, v77
	v_cvt_pk_bf16_f32 v34, v32, s0
	v_lshl_add_u64 v[32:33], v[62:63], 0, v[56:57]
; __device__ __forceinline__ unsigned f2bf(float f) { return pk2(f, 0.f) & 0xffffu; }
; __device__ __forceinline__ int crow(int r, int hi) { return (r & 3) + 8 * (r >> 2) + 4 * hi; }
; template <bool DIFF>
; __device__ __forceinline__ void attn_unit_coop(const Grp& G, int b, int h, int qb, int n, LAS unsigned char* lds, const int tid_in) {
;     ...
;         bf16* obase = (DIFF ? (n == 0 ? G.DO : G.XN) + h * 128 : G.MO + h * 64) + (seq0 + qrow0) * 1024 + q;
; #pragma unroll
;         for (int db = 0; db < NDB; ++db)
; #pragma unroll
;             for (int r = 0; r < 16; ++r) obase[(size_t)crow(r, hi) * 1024 + db * 32] = (bf16)f2bf(st.o[db][r] * inv[r]);
	global_store_short v[32:33], v34, off
	v_mul_f32_e32 v32, v42, v78
	v_cvt_pk_bf16_f32 v34, v32, s0
	v_lshl_add_u64 v[32:33], v[62:63], 0, v[86:87]
	global_store_short v[32:33], v34, off
	v_mul_f32_e32 v32, v43, v79
	v_cvt_pk_bf16_f32 v34, v32, s0
	v_lshl_add_u64 v[32:33], v[62:63], 0, v[58:59]
	global_store_short v[32:33], v34, off
	v_mul_f32_e32 v32, v44, v94
	v_cvt_pk_bf16_f32 v34, v32, s0
	v_lshl_add_u64 v[32:33], v[62:63], 0, v[88:89]
	global_store_short v[32:33], v34, off
	v_mul_f32_e32 v32, v45, v95
	v_cvt_pk_bf16_f32 v34, v32, s0
	v_lshl_add_u64 v[32:33], v[62:63], 0, v[60:61]
	global_store_short v[32:33], v34, off
	v_mul_f32_e32 v32, v46, v96
	v_cvt_pk_bf16_f32 v34, v32, s0
	v_lshl_add_u64 v[32:33], v[62:63], 0, v[90:91]
	v_cvt_pk_bf16_f32 v16, v16, s0
	global_store_short v[32:33], v34, off
	v_mul_f32_e32 v32, v47, v97
	global_store_short v[66:67], v16, off offset:128
	v_mul_f32_e32 v16, v17, v69
	v_cvt_pk_bf16_f32 v34, v32, s0
	v_lshl_add_u64 v[32:33], v[62:63], 0, v[184:185]
	v_cvt_pk_bf16_f32 v16, v16, s0
	global_store_short v[32:33], v34, off
	v_lshl_add_u64 v[32:33], v[64:65], 0, s[94:95]
	global_store_short v[66:67], v16, off offset:2176
	v_mul_f32_e32 v16, v18, v70
	v_cvt_pk_bf16_f32 v18, v16, s0
	v_lshl_add_u64 v[16:17], v[32:33], 0, v[48:49]
	global_store_short v[16:17], v18, off
	v_mul_f32_e32 v16, v19, v71
	v_cvt_pk_bf16_f32 v18, v16, s0
	v_lshl_add_u64 v[16:17], v[32:33], 0, v[50:51]
	global_store_short v[16:17], v18, off
	v_mul_f32_e32 v16, v20, v72
	v_cvt_pk_bf16_f32 v18, v16, s0
	v_lshl_add_u64 v[16:17], v[32:33], 0, v[80:81]
	global_store_short v[16:17], v18, off
	v_mul_f32_e32 v16, v21, v73
	v_cvt_pk_bf16_f32 v18, v16, s0
	v_lshl_add_u64 v[16:17], v[32:33], 0, v[52:53]
	global_store_short v[16:17], v18, off
	v_mul_f32_e32 v16, v22, v74
	v_cvt_pk_bf16_f32 v18, v16, s0
	v_lshl_add_u64 v[16:17], v[32:33], 0, v[82:83]
	global_store_short v[16:17], v18, off
	v_mul_f32_e32 v16, v23, v75
	v_cvt_pk_bf16_f32 v18, v16, s0
	v_lshl_add_u64 v[16:17], v[32:33], 0, v[54:55]
	global_store_short v[16:17], v18, off
	v_mul_f32_e32 v16, v24, v76
	v_cvt_pk_bf16_f32 v18, v16, s0
	v_lshl_add_u64 v[16:17], v[32:33], 0, v[84:85]
	global_store_short v[16:17], v18, off
	v_mul_f32_e32 v16, v25, v77
	v_cvt_pk_bf16_f32 v18, v16, s0
	v_lshl_add_u64 v[16:17], v[32:33], 0, v[56:57]
	global_store_short v[16:17], v18, off
	v_mul_f32_e32 v16, v26, v78
	v_cvt_pk_bf16_f32 v18, v16, s0
	v_lshl_add_u64 v[16:17], v[32:33], 0, v[86:87]
	global_store_short v[16:17], v18, off
	v_mul_f32_e32 v16, v27, v79
	v_cvt_pk_bf16_f32 v18, v16, s0
	v_lshl_add_u64 v[16:17], v[32:33], 0, v[58:59]
	global_store_short v[16:17], v18, off
	v_mul_f32_e32 v16, v28, v94
	v_cvt_pk_bf16_f32 v18, v16, s0
	v_lshl_add_u64 v[16:17], v[32:33], 0, v[88:89]
	global_store_short v[16:17], v18, off
	v_mul_f32_e32 v16, v29, v95
	v_cvt_pk_bf16_f32 v18, v16, s0
	v_lshl_add_u64 v[16:17], v[32:33], 0, v[60:61]
	global_store_short v[16:17], v18, off
	v_mul_f32_e32 v16, v30, v96
	v_cvt_pk_bf16_f32 v18, v16, s0
	v_lshl_add_u64 v[16:17], v[32:33], 0, v[90:91]
	global_store_short v[16:17], v18, off
	v_mul_f32_e32 v16, v31, v97
	v_cvt_pk_bf16_f32 v18, v16, s0
	s_mov_b64 s[0:1], 0xc0
	v_cvt_pk_bf16_f32 v0, v0, s0
	global_store_short v[66:67], v0, off offset:192
	v_mul_f32_e32 v0, v1, v69
	v_lshl_add_u64 v[16:17], v[32:33], 0, v[184:185]
	v_cvt_pk_bf16_f32 v0, v0, s0
	global_store_short v[16:17], v18, off
	v_lshl_add_u64 v[16:17], v[64:65], 0, s[0:1]
	global_store_short v[66:67], v0, off offset:2240
	v_mul_f32_e32 v0, v2, v70
	v_cvt_pk_bf16_f32 v2, v0, s0
	v_lshl_add_u64 v[0:1], v[16:17], 0, v[48:49]
	global_store_short v[0:1], v2, off
	v_mul_f32_e32 v0, v3, v71
	v_cvt_pk_bf16_f32 v2, v0, s0
	v_lshl_add_u64 v[0:1], v[16:17], 0, v[50:51]
	global_store_short v[0:1], v2, off
	v_mul_f32_e32 v0, v4, v72
	v_cvt_pk_bf16_f32 v2, v0, s0
	v_lshl_add_u64 v[0:1], v[16:17], 0, v[80:81]
	global_store_short v[0:1], v2, off
	v_mul_f32_e32 v0, v5, v73
	v_cvt_pk_bf16_f32 v2, v0, s0
	v_lshl_add_u64 v[0:1], v[16:17], 0, v[52:53]
	global_store_short v[0:1], v2, off
	v_mul_f32_e32 v0, v6, v74
	v_cvt_pk_bf16_f32 v2, v0, s0
	v_lshl_add_u64 v[0:1], v[16:17], 0, v[82:83]
	global_store_short v[0:1], v2, off
	v_mul_f32_e32 v0, v7, v75
	v_cvt_pk_bf16_f32 v2, v0, s0
	v_lshl_add_u64 v[0:1], v[16:17], 0, v[54:55]
	global_store_short v[0:1], v2, off
	v_mul_f32_e32 v0, v8, v76
	v_cvt_pk_bf16_f32 v2, v0, s0
	v_lshl_add_u64 v[0:1], v[16:17], 0, v[84:85]
	global_store_short v[0:1], v2, off
	v_mul_f32_e32 v0, v9, v77
	v_cvt_pk_bf16_f32 v2, v0, s0
	v_lshl_add_u64 v[0:1], v[16:17], 0, v[56:57]
	global_store_short v[0:1], v2, off
	v_mul_f32_e32 v0, v10, v78
	v_cvt_pk_bf16_f32 v2, v0, s0
	v_lshl_add_u64 v[0:1], v[16:17], 0, v[86:87]
	global_store_short v[0:1], v2, off
	v_mul_f32_e32 v0, v11, v79
	v_cvt_pk_bf16_f32 v2, v0, s0
	v_lshl_add_u64 v[0:1], v[16:17], 0, v[58:59]
	global_store_short v[0:1], v2, off
	v_mul_f32_e32 v0, v12, v94
	v_cvt_pk_bf16_f32 v2, v0, s0
	v_lshl_add_u64 v[0:1], v[16:17], 0, v[88:89]
	global_store_short v[0:1], v2, off
	v_mul_f32_e32 v0, v13, v95
	v_cvt_pk_bf16_f32 v2, v0, s0
	v_lshl_add_u64 v[0:1], v[16:17], 0, v[60:61]
	global_store_short v[0:1], v2, off
	v_mul_f32_e32 v0, v14, v96
	v_cvt_pk_bf16_f32 v2, v0, s0
	v_lshl_add_u64 v[0:1], v[16:17], 0, v[90:91]
	global_store_short v[0:1], v2, off
	v_mul_f32_e32 v0, v15, v97
	v_cvt_pk_bf16_f32 v2, v0, s0
	v_lshl_add_u64 v[0:1], v[16:17], 0, v[184:185]
	s_mov_b64 s[0:1], 0
	s_and_b64 vcc, exec, s[36:37]
	global_store_short v[0:1], v2, off
	s_cbranch_vccnz .LBB0_516

; __device__ __forceinline__ unsigned pk2(float lo, float hi) { f32x2 v = {lo, hi}; bf16x2_hw b = __builtin_convertvector(v, bf16x2_hw); return __builtin_bit_cast(unsigned, b); }
; __device__ __forceinline__ void diffmix_block(const Grp& G, int b, int h, int qb, float lam, const float* subln, int tid) {
;     const int lane = tid & 63, wid = tid >> 6;
;     const float g0 = subln[2 * lane] * 0.8f, g1 = subln[2 * lane + 1] * 0.8f;
;     const size_t row0 = (size_t)b * TS + qb * 256 + wid * 32;
; #pragma unroll 1
;     for (int rb = 0; rb < 32; rb += 16) {
;         unsigned a[16], c[16];
; #pragma unroll
;         for (int r = 0; r < 16; ++r) { a[r] = *((const unsigned*)(G.DO + (row0 + rb + r) * 1024 + h * 128) + lane); c[r] = *((const unsigned*)(G.XN + (row0 + rb + r) * 1024 + h * 128) + lane); }
; #pragma unroll
;         for (int r = 0; r < 16; ++r) {
;             const float v0 = bflo(a[r]) - lam * bflo(c[r]), v1 = bfhi(a[r]) - lam * bfhi(c[r]);
;             const float ss = wave_sum(v0 * v0 + v1 * v1);
;             const float rs = 1.0f / sqrtf(ss * (1.f / 128.f) + EPSN);
;             *((unsigned*)(G.DO + (row0 + rb + r) * 1024 + h * 128) + lane) = pk2(v0 * rs * g0, v1 * rs * g1);
;         }
;     }
; }
.LBB0_555:
	v_or_b32_e32 v11, s1, v9
	v_or_b32_e32 v10, s0, v8
	v_lshlrev_b64 v[50:51], 11, v[10:11]
	v_lshl_add_u64 v[52:53], v[2:3], 0, v[50:51]
	v_lshl_add_u64 v[10:11], v[4:5], 0, v[50:51]
	global_load_dword v59, v[52:53], off
	global_load_dword v60, v[10:11], off
	v_or_b32_e32 v10, 0x800, v50
	v_mov_b32_e32 v11, v51
	v_lshl_add_u64 v[54:55], v[2:3], 0, v[10:11]
	v_lshl_add_u64 v[10:11], v[4:5], 0, v[10:11]
	global_load_dword v61, v[54:55], off
	global_load_dword v62, v[10:11], off
	v_or_b32_e32 v10, 0x1000, v50
	v_mov_b32_e32 v11, v51
	v_lshl_add_u64 v[56:57], v[2:3], 0, v[10:11]
	v_lshl_add_u64 v[10:11], v[4:5], 0, v[10:11]
	global_load_dword v63, v[56:57], off
	global_load_dword v64, v[10:11], off
	v_or_b32_e32 v10, 0x1800, v50
	v_mov_b32_e32 v11, v51
	v_lshl_add_u64 v[34:35], v[2:3], 0, v[10:11]
	v_lshl_add_u64 v[10:11], v[4:5], 0, v[10:11]
	global_load_dword v65, v[34:35], off
	global_load_dword v66, v[10:11], off
	v_or_b32_e32 v10, 0x2000, v50
	v_mov_b32_e32 v11, v51
	v_lshl_add_u64 v[32:33], v[2:3], 0, v[10:11]
	v_lshl_add_u64 v[10:11], v[4:5], 0, v[10:11]
	global_load_dword v67, v[32:33], off
	global_load_dword v68, v[10:11], off
	v_or_b32_e32 v10, 0x2800, v50
	v_mov_b32_e32 v11, v51
	v_lshl_add_u64 v[30:31], v[2:3], 0, v[10:11]
	v_lshl_add_u64 v[10:11], v[4:5], 0, v[10:11]
	global_load_dword v69, v[30:31], off
	global_load_dword v70, v[10:11], off
	v_or_b32_e32 v10, 0x3000, v50
	v_mov_b32_e32 v11, v51
	v_lshl_add_u64 v[28:29], v[2:3], 0, v[10:11]
	v_lshl_add_u64 v[10:11], v[4:5], 0, v[10:11]
	global_load_dword v71, v[28:29], off
	global_load_dword v72, v[10:11], off
	v_or_b32_e32 v10, 0x3800, v50
	v_mov_b32_e32 v11, v51
	v_lshl_add_u64 v[26:27], v[2:3], 0, v[10:11]
	v_lshl_add_u64 v[10:11], v[4:5], 0, v[10:11]
	global_load_dword v73, v[26:27], off
	global_load_dword v74, v[10:11], off
	v_or_b32_e32 v10, 0x4000, v50
	v_mov_b32_e32 v11, v51
	v_lshl_add_u64 v[24:25], v[2:3], 0, v[10:11]
	v_lshl_add_u64 v[10:11], v[4:5], 0, v[10:11]
	global_load_dword v75, v[24:25], off
	global_load_dword v76, v[10:11], off
	v_or_b32_e32 v10, 0x4800, v50
	v_mov_b32_e32 v11, v51
	v_lshl_add_u64 v[22:23], v[2:3], 0, v[10:11]
	v_lshl_add_u64 v[10:11], v[4:5], 0, v[10:11]
	global_load_dword v48, v[22:23], off
	global_load_dword v49, v[10:11], off
	v_or_b32_e32 v10, 0x5000, v50
	v_mov_b32_e32 v11, v51
	v_lshl_add_u64 v[20:21], v[2:3], 0, v[10:11]
	v_lshl_add_u64 v[10:11], v[4:5], 0, v[10:11]
	global_load_dword v46, v[20:21], off
	global_load_dword v47, v[10:11], off
	v_or_b32_e32 v10, 0x5800, v50
	v_mov_b32_e32 v11, v51
	v_lshl_add_u64 v[18:19], v[2:3], 0, v[10:11]
	v_lshl_add_u64 v[10:11], v[4:5], 0, v[10:11]
	global_load_dword v44, v[18:19], off
	global_load_dword v45, v[10:11], off
	v_or_b32_e32 v10, 0x6000, v50
	v_mov_b32_e32 v11, v51
	v_lshl_add_u64 v[16:17], v[2:3], 0, v[10:11]
	v_lshl_add_u64 v[10:11], v[4:5], 0, v[10:11]
	global_load_dword v42, v[16:17], off
	global_load_dword v43, v[10:11], off
	v_or_b32_e32 v10, 0x6800, v50
	v_mov_b32_e32 v11, v51
	v_lshl_add_u64 v[14:15], v[2:3], 0, v[10:11]
	v_lshl_add_u64 v[10:11], v[4:5], 0, v[10:11]
	global_load_dword v40, v[14:15], off
	global_load_dword v41, v[10:11], off
	v_or_b32_e32 v10, 0x7000, v50
	v_mov_b32_e32 v11, v51
	v_lshl_add_u64 v[12:13], v[2:3], 0, v[10:11]
	v_lshl_add_u64 v[10:11], v[4:5], 0, v[10:11]
	v_or_b32_e32 v50, 0x7800, v50
	global_load_dword v38, v[12:13], off
	global_load_dword v39, v[10:11], off
	v_lshl_add_u64 v[10:11], v[2:3], 0, v[50:51]
	v_lshl_add_u64 v[50:51], v[4:5], 0, v[50:51]
	global_load_dword v36, v[10:11], off
	global_load_dword v37, v[50:51], off
	s_waitcnt vmcnt(31)
	v_lshlrev_b32_e32 v50, 16, v59
	s_waitcnt vmcnt(30)
	v_lshlrev_b32_e32 v58, 16, v60
	v_and_b32_e32 v51, 0xffff0000, v59
	v_and_b32_e32 v59, 0xffff0000, v60
	v_pk_fma_f32 v[50:51], v[192:193], v[58:59], v[50:51] neg_lo:[1,0,0] neg_hi:[1,0,0]
	s_nop 0
	v_pk_mul_f32 v[58:59], v[50:51], v[50:51]
	s_nop 0
	v_add_f32_e32 v58, v58, v59
	ds_swizzle_b32 v59, v58 offset:swizzle(SWAP,1)
	s_waitcnt lgkmcnt(0)
	v_add_f32_e32 v58, v58, v59
	ds_swizzle_b32 v59, v58 offset:swizzle(SWAP,2)
	s_waitcnt lgkmcnt(0)
	v_add_f32_e32 v58, v58, v59
	ds_swizzle_b32 v59, v58 offset:swizzle(SWAP,4)
	s_waitcnt lgkmcnt(0)
	v_add_f32_e32 v58, v58, v59
	ds_swizzle_b32 v59, v58 offset:swizzle(SWAP,8)
	s_waitcnt lgkmcnt(0)
	v_add_f32_e32 v58, v58, v59
	ds_swizzle_b32 v59, v58 offset:swizzle(SWAP,16)
	s_waitcnt lgkmcnt(0)
	v_add_f32_e32 v58, v58, v59
	v_mov_b32_e32 v59, v58
	s_nop 1
	v_permlane32_swap_b32_e32 v58, v59
	v_add_f32_e32 v58, v58, v59
	v_fmamk_f32 v58, v58, 0x3c000000, v205
	v_cmp_gt_f32_e32 vcc, s63, v58
	v_mul_f32_e32 v59, 0x4f800000, v58
	s_nop 0
	v_cndmask_b32_e32 v58, v58, v59, vcc
	v_sqrt_f32_e32 v59, v58
	s_nop 0
	v_add_u32_e32 v60, -1, v59
	v_fma_f32 v77, -v60, v59, v58
	v_cmp_ge_f32_e64 s[0:1], 0, v77
	v_add_u32_e32 v77, 1, v59
	s_nop 0
	v_cndmask_b32_e64 v60, v59, v60, s[0:1]
	v_fma_f32 v59, -v77, v59, v58
	v_cmp_lt_f32_e64 s[0:1], 0, v59
	s_nop 1
	v_cndmask_b32_e64 v59, v60, v77, s[0:1]
	v_mul_f32_e32 v60, 0x37800000, v59
	v_cndmask_b32_e32 v59, v59, v60, vcc
	v_cmp_class_f32_e32 vcc, v58, v206
	s_nop 1
	v_cndmask_b32_e32 v58, v59, v58, vcc
	v_rcp_f32_e32 v58, v58
	s_nop 0
	v_pk_mul_f32 v[50:51], v[50:51], v[58:59] op_sel_hi:[1,0]
	s_nop 0
	v_pk_mul_f32 v[50:51], v[0:1], v[50:51]
	s_nop 0
	v_cvt_pk_bf16_f32 v50, v50, v51
	global_store_dword v[52:53], v50, off
	s_waitcnt vmcnt(30)
	v_lshlrev_b32_e32 v50, 16, v61
	s_waitcnt vmcnt(29)
	v_lshlrev_b32_e32 v52, 16, v62
	v_and_b32_e32 v51, 0xffff0000, v61
	v_and_b32_e32 v53, 0xffff0000, v62
	v_pk_fma_f32 v[50:51], v[192:193], v[52:53], v[50:51] neg_lo:[1,0,0] neg_hi:[1,0,0]
	s_nop 0
	v_pk_mul_f32 v[52:53], v[50:51], v[50:51]
	s_nop 0
	v_add_f32_e32 v52, v52, v53
	ds_swizzle_b32 v53, v52 offset:swizzle(SWAP,1)
	s_waitcnt lgkmcnt(0)
; __device__ __forceinline__ unsigned pk2(float lo, float hi) { f32x2 v = {lo, hi}; bf16x2_hw b = __builtin_convertvector(v, bf16x2_hw); return __builtin_bit_cast(unsigned, b); }
; __device__ __forceinline__ void diffmix_block(const Grp& G, int b, int h, int qb, float lam, const float* subln, int tid) {
;     ...
;         for (int r = 0; r < 16; ++r) {
;             const float v0 = bflo(a[r]) - lam * bflo(c[r]), v1 = bfhi(a[r]) - lam * bfhi(c[r]);
;             const float ss = wave_sum(v0 * v0 + v1 * v1);
;             const float rs = 1.0f / sqrtf(ss * (1.f / 128.f) + EPSN);
;             *((unsigned*)(G.DO + (row0 + rb + r) * 1024 + h * 128) + lane) = pk2(v0 * rs * g0, v1 * rs * g1);
;         }
	v_add_f32_e32 v52, v52, v53
	ds_swizzle_b32 v53, v52 offset:swizzle(SWAP,2)
	s_waitcnt lgkmcnt(0)
	v_add_f32_e32 v52, v52, v53
	ds_swizzle_b32 v53, v52 offset:swizzle(SWAP,4)
	s_waitcnt lgkmcnt(0)
	v_add_f32_e32 v52, v52, v53
	ds_swizzle_b32 v53, v52 offset:swizzle(SWAP,8)
	s_waitcnt lgkmcnt(0)
	v_add_f32_e32 v52, v52, v53
	ds_swizzle_b32 v53, v52 offset:swizzle(SWAP,16)
	s_waitcnt lgkmcnt(0)
	v_add_f32_e32 v52, v52, v53
	v_mov_b32_e32 v53, v52
	s_nop 1
	v_permlane32_swap_b32_e32 v52, v53
	v_add_f32_e32 v52, v52, v53
	v_fmamk_f32 v52, v52, 0x3c000000, v205
	v_cmp_gt_f32_e32 vcc, s63, v52
	v_mul_f32_e32 v53, 0x4f800000, v52
	s_nop 0
	v_cndmask_b32_e32 v52, v52, v53, vcc
	v_sqrt_f32_e32 v53, v52
	s_nop 0
	v_add_u32_e32 v58, -1, v53
	v_fma_f32 v59, -v58, v53, v52
	v_cmp_ge_f32_e64 s[0:1], 0, v59
	v_add_u32_e32 v59, 1, v53
	s_nop 0
	v_cndmask_b32_e64 v58, v53, v58, s[0:1]
	v_fma_f32 v53, -v59, v53, v52
	v_cmp_lt_f32_e64 s[0:1], 0, v53
	s_nop 1
	v_cndmask_b32_e64 v53, v58, v59, s[0:1]
	v_mul_f32_e32 v58, 0x37800000, v53
	v_cndmask_b32_e32 v53, v53, v58, vcc
	v_cmp_class_f32_e32 vcc, v52, v206
	s_nop 1
	v_cndmask_b32_e32 v52, v53, v52, vcc
	v_rcp_f32_e32 v52, v52
	s_nop 0
	v_pk_mul_f32 v[50:51], v[50:51], v[52:53] op_sel_hi:[1,0]
	s_waitcnt vmcnt(27)
	v_lshlrev_b32_e32 v52, 16, v64
	v_pk_mul_f32 v[50:51], v[0:1], v[50:51]
	v_and_b32_e32 v53, 0xffff0000, v64
	v_cvt_pk_bf16_f32 v50, v50, v51
	global_store_dword v[54:55], v50, off
	v_lshlrev_b32_e32 v50, 16, v63
	v_and_b32_e32 v51, 0xffff0000, v63
	v_pk_fma_f32 v[50:51], v[192:193], v[52:53], v[50:51] neg_lo:[1,0,0] neg_hi:[1,0,0]
	s_nop 0
	v_pk_mul_f32 v[52:53], v[50:51], v[50:51]
	s_nop 0
	v_add_f32_e32 v52, v52, v53
	ds_swizzle_b32 v53, v52 offset:swizzle(SWAP,1)
	s_waitcnt lgkmcnt(0)
	v_add_f32_e32 v52, v52, v53
	ds_swizzle_b32 v53, v52 offset:swizzle(SWAP,2)
	s_waitcnt lgkmcnt(0)
	v_add_f32_e32 v52, v52, v53
	ds_swizzle_b32 v53, v52 offset:swizzle(SWAP,4)
	s_waitcnt lgkmcnt(0)
	v_add_f32_e32 v52, v52, v53
	ds_swizzle_b32 v53, v52 offset:swizzle(SWAP,8)
	s_waitcnt lgkmcnt(0)
	v_add_f32_e32 v52, v52, v53
	ds_swizzle_b32 v53, v52 offset:swizzle(SWAP,16)
	s_waitcnt lgkmcnt(0)
	v_add_f32_e32 v52, v52, v53
	v_mov_b32_e32 v53, v52
	s_nop 1
	v_permlane32_swap_b32_e32 v52, v53
	v_add_f32_e32 v52, v52, v53
	v_fmamk_f32 v52, v52, 0x3c000000, v205
	v_cmp_gt_f32_e32 vcc, s63, v52
	v_mul_f32_e32 v53, 0x4f800000, v52
	s_nop 0
	v_cndmask_b32_e32 v52, v52, v53, vcc
	v_sqrt_f32_e32 v53, v52
	s_nop 0
	v_add_u32_e32 v54, -1, v53
	v_fma_f32 v55, -v54, v53, v52
	v_cmp_ge_f32_e64 s[0:1], 0, v55
	v_add_u32_e32 v55, 1, v53
	s_nop 0
	v_cndmask_b32_e64 v54, v53, v54, s[0:1]
	v_fma_f32 v53, -v55, v53, v52
	v_cmp_lt_f32_e64 s[0:1], 0, v53
	s_nop 1
	v_cndmask_b32_e64 v53, v54, v55, s[0:1]
	v_mul_f32_e32 v54, 0x37800000, v53
	v_cndmask_b32_e32 v53, v53, v54, vcc
	v_cmp_class_f32_e32 vcc, v52, v206
	s_nop 1
	v_cndmask_b32_e32 v52, v53, v52, vcc
	v_rcp_f32_e32 v52, v52
	s_nop 0
	v_pk_mul_f32 v[50:51], v[50:51], v[52:53] op_sel_hi:[1,0]
	s_waitcnt vmcnt(26)
	v_lshlrev_b32_e32 v52, 16, v66
	v_pk_mul_f32 v[50:51], v[0:1], v[50:51]
	v_and_b32_e32 v53, 0xffff0000, v66
	v_cvt_pk_bf16_f32 v50, v50, v51
	global_store_dword v[56:57], v50, off
	v_lshlrev_b32_e32 v50, 16, v65
	v_and_b32_e32 v51, 0xffff0000, v65
	v_pk_fma_f32 v[50:51], v[192:193], v[52:53], v[50:51] neg_lo:[1,0,0] neg_hi:[1,0,0]
	s_nop 0
	v_pk_mul_f32 v[52:53], v[50:51], v[50:51]
	s_nop 0
	v_add_f32_e32 v52, v52, v53
	ds_swizzle_b32 v53, v52 offset:swizzle(SWAP,1)
	s_waitcnt lgkmcnt(0)
	v_add_f32_e32 v52, v52, v53
	ds_swizzle_b32 v53, v52 offset:swizzle(SWAP,2)
	s_waitcnt lgkmcnt(0)
	v_add_f32_e32 v52, v52, v53
	ds_swizzle_b32 v53, v52 offset:swizzle(SWAP,4)
	s_waitcnt lgkmcnt(0)
	v_add_f32_e32 v52, v52, v53
	ds_swizzle_b32 v53, v52 offset:swizzle(SWAP,8)
	s_waitcnt lgkmcnt(0)
	v_add_f32_e32 v52, v52, v53
	ds_swizzle_b32 v53, v52 offset:swizzle(SWAP,16)
	s_waitcnt lgkmcnt(0)
	v_add_f32_e32 v52, v52, v53
	v_mov_b32_e32 v53, v52
	s_nop 1
	v_permlane32_swap_b32_e32 v52, v53
	v_add_f32_e32 v52, v52, v53
	v_fmamk_f32 v52, v52, 0x3c000000, v205
	v_cmp_gt_f32_e32 vcc, s63, v52
	v_mul_f32_e32 v53, 0x4f800000, v52
	s_nop 0
	v_cndmask_b32_e32 v52, v52, v53, vcc
	v_sqrt_f32_e32 v53, v52
	s_nop 0
	v_add_u32_e32 v54, -1, v53
	v_fma_f32 v55, -v54, v53, v52
	v_cmp_ge_f32_e64 s[0:1], 0, v55
	v_add_u32_e32 v55, 1, v53
	s_nop 0
	v_cndmask_b32_e64 v54, v53, v54, s[0:1]
	v_fma_f32 v53, -v55, v53, v52
	v_cmp_lt_f32_e64 s[0:1], 0, v53
	s_nop 1
	v_cndmask_b32_e64 v53, v54, v55, s[0:1]
	v_mul_f32_e32 v54, 0x37800000, v53
	v_cndmask_b32_e32 v53, v53, v54, vcc
	v_cmp_class_f32_e32 vcc, v52, v206
	s_nop 1
	v_cndmask_b32_e32 v52, v53, v52, vcc
	v_rcp_f32_e32 v52, v52
	s_nop 0
	v_pk_mul_f32 v[50:51], v[50:51], v[52:53] op_sel_hi:[1,0]
	s_nop 0
	v_pk_mul_f32 v[50:51], v[0:1], v[50:51]
	s_nop 0
	v_cvt_pk_bf16_f32 v50, v50, v51
	global_store_dword v[34:35], v50, off
	s_waitcnt vmcnt(27)
	v_lshlrev_b32_e32 v34, 16, v67
	s_waitcnt vmcnt(26)
	v_lshlrev_b32_e32 v50, 16, v68
	v_and_b32_e32 v35, 0xffff0000, v67
	v_and_b32_e32 v51, 0xffff0000, v68
	v_pk_fma_f32 v[34:35], v[192:193], v[50:51], v[34:35] neg_lo:[1,0,0] neg_hi:[1,0,0]
	s_nop 0
	v_pk_mul_f32 v[50:51], v[34:35], v[34:35]
	s_nop 0
	v_add_f32_e32 v50, v50, v51
	ds_swizzle_b32 v51, v50 offset:swizzle(SWAP,1)
	s_waitcnt lgkmcnt(0)
	v_add_f32_e32 v50, v50, v51
	ds_swizzle_b32 v51, v50 offset:swizzle(SWAP,2)
	s_waitcnt lgkmcnt(0)
	v_add_f32_e32 v50, v50, v51
	ds_swizzle_b32 v51, v50 offset:swizzle(SWAP,4)
	s_waitcnt lgkmcnt(0)
	v_add_f32_e32 v50, v50, v51
	ds_swizzle_b32 v51, v50 offset:swizzle(SWAP,8)
	s_waitcnt lgkmcnt(0)
; __device__ __forceinline__ unsigned pk2(float lo, float hi) { f32x2 v = {lo, hi}; bf16x2_hw b = __builtin_convertvector(v, bf16x2_hw); return __builtin_bit_cast(unsigned, b); }
; __device__ __forceinline__ void diffmix_block(const Grp& G, int b, int h, int qb, float lam, const float* subln, int tid) {
;     ...
;         for (int r = 0; r < 16; ++r) {
;             const float v0 = bflo(a[r]) - lam * bflo(c[r]), v1 = bfhi(a[r]) - lam * bfhi(c[r]);
;             const float ss = wave_sum(v0 * v0 + v1 * v1);
;             const float rs = 1.0f / sqrtf(ss * (1.f / 128.f) + EPSN);
;             *((unsigned*)(G.DO + (row0 + rb + r) * 1024 + h * 128) + lane) = pk2(v0 * rs * g0, v1 * rs * g1);
;         }
	v_add_f32_e32 v50, v50, v51
	ds_swizzle_b32 v51, v50 offset:swizzle(SWAP,16)
	s_waitcnt lgkmcnt(0)
	v_add_f32_e32 v50, v50, v51
	v_mov_b32_e32 v51, v50
	s_nop 1
	v_permlane32_swap_b32_e32 v50, v51
	v_add_f32_e32 v50, v50, v51
	v_fmamk_f32 v50, v50, 0x3c000000, v205
	v_cmp_gt_f32_e32 vcc, s63, v50
	v_mul_f32_e32 v51, 0x4f800000, v50
	s_nop 0
	v_cndmask_b32_e32 v50, v50, v51, vcc
	v_sqrt_f32_e32 v51, v50
	s_nop 0
	v_add_u32_e32 v52, -1, v51
	v_fma_f32 v53, -v52, v51, v50
	v_cmp_ge_f32_e64 s[0:1], 0, v53
	v_add_u32_e32 v53, 1, v51
	s_nop 0
	v_cndmask_b32_e64 v52, v51, v52, s[0:1]
	v_fma_f32 v51, -v53, v51, v50
	v_cmp_lt_f32_e64 s[0:1], 0, v51
	s_nop 1
	v_cndmask_b32_e64 v51, v52, v53, s[0:1]
	v_mul_f32_e32 v52, 0x37800000, v51
	v_cndmask_b32_e32 v51, v51, v52, vcc
	v_cmp_class_f32_e32 vcc, v50, v206
	s_nop 1
	v_cndmask_b32_e32 v50, v51, v50, vcc
	v_rcp_f32_e32 v50, v50
	s_nop 0
	v_pk_mul_f32 v[34:35], v[34:35], v[50:51] op_sel_hi:[1,0]
	s_nop 0
	v_pk_mul_f32 v[34:35], v[0:1], v[34:35]
	s_nop 0
	v_cvt_pk_bf16_f32 v34, v34, v35
	global_store_dword v[32:33], v34, off
	s_waitcnt vmcnt(26)
	v_lshlrev_b32_e32 v32, 16, v69
	s_waitcnt vmcnt(25)
	v_lshlrev_b32_e32 v34, 16, v70
	v_and_b32_e32 v33, 0xffff0000, v69
	v_and_b32_e32 v35, 0xffff0000, v70
	v_pk_fma_f32 v[32:33], v[192:193], v[34:35], v[32:33] neg_lo:[1,0,0] neg_hi:[1,0,0]
	s_nop 0
	v_pk_mul_f32 v[34:35], v[32:33], v[32:33]
	s_nop 0
	v_add_f32_e32 v34, v34, v35
	ds_swizzle_b32 v35, v34 offset:swizzle(SWAP,1)
	s_waitcnt lgkmcnt(0)
	v_add_f32_e32 v34, v34, v35
	ds_swizzle_b32 v35, v34 offset:swizzle(SWAP,2)
	s_waitcnt lgkmcnt(0)
	v_add_f32_e32 v34, v34, v35
	ds_swizzle_b32 v35, v34 offset:swizzle(SWAP,4)
	s_waitcnt lgkmcnt(0)
	v_add_f32_e32 v34, v34, v35
	ds_swizzle_b32 v35, v34 offset:swizzle(SWAP,8)
	s_waitcnt lgkmcnt(0)
	v_add_f32_e32 v34, v34, v35
	ds_swizzle_b32 v35, v34 offset:swizzle(SWAP,16)
	s_waitcnt lgkmcnt(0)
	v_add_f32_e32 v34, v34, v35
	v_mov_b32_e32 v35, v34
	s_nop 1
	v_permlane32_swap_b32_e32 v34, v35
	v_add_f32_e32 v34, v34, v35
	v_fmamk_f32 v34, v34, 0x3c000000, v205
	v_cmp_gt_f32_e32 vcc, s63, v34
	v_mul_f32_e32 v35, 0x4f800000, v34
	s_nop 0
	v_cndmask_b32_e32 v34, v34, v35, vcc
	v_sqrt_f32_e32 v35, v34
	s_nop 0
	v_add_u32_e32 v50, -1, v35
	v_fma_f32 v51, -v50, v35, v34
	v_cmp_ge_f32_e64 s[0:1], 0, v51
	v_add_u32_e32 v51, 1, v35
	s_nop 0
	v_cndmask_b32_e64 v50, v35, v50, s[0:1]
	v_fma_f32 v35, -v51, v35, v34
	v_cmp_lt_f32_e64 s[0:1], 0, v35
	s_nop 1
	v_cndmask_b32_e64 v35, v50, v51, s[0:1]
	v_mul_f32_e32 v50, 0x37800000, v35
	v_cndmask_b32_e32 v35, v35, v50, vcc
	v_cmp_class_f32_e32 vcc, v34, v206
	s_nop 1
	v_cndmask_b32_e32 v34, v35, v34, vcc
	v_rcp_f32_e32 v34, v34
	s_nop 0
	v_pk_mul_f32 v[32:33], v[32:33], v[34:35] op_sel_hi:[1,0]
	s_nop 0
	v_pk_mul_f32 v[32:33], v[0:1], v[32:33]
	s_nop 0
	v_cvt_pk_bf16_f32 v32, v32, v33
	global_store_dword v[30:31], v32, off
	s_waitcnt vmcnt(25)
	v_lshlrev_b32_e32 v30, 16, v71
	s_waitcnt vmcnt(24)
	v_lshlrev_b32_e32 v32, 16, v72
	v_and_b32_e32 v31, 0xffff0000, v71
	v_and_b32_e32 v33, 0xffff0000, v72
	v_pk_fma_f32 v[30:31], v[192:193], v[32:33], v[30:31] neg_lo:[1,0,0] neg_hi:[1,0,0]
	s_nop 0
	v_pk_mul_f32 v[32:33], v[30:31], v[30:31]
	s_nop 0
	v_add_f32_e32 v32, v32, v33
	ds_swizzle_b32 v33, v32 offset:swizzle(SWAP,1)
	s_waitcnt lgkmcnt(0)
	v_add_f32_e32 v32, v32, v33
	ds_swizzle_b32 v33, v32 offset:swizzle(SWAP,2)
	s_waitcnt lgkmcnt(0)
	v_add_f32_e32 v32, v32, v33
	ds_swizzle_b32 v33, v32 offset:swizzle(SWAP,4)
	s_waitcnt lgkmcnt(0)
	v_add_f32_e32 v32, v32, v33
	ds_swizzle_b32 v33, v32 offset:swizzle(SWAP,8)
	s_waitcnt lgkmcnt(0)
	v_add_f32_e32 v32, v32, v33
	ds_swizzle_b32 v33, v32 offset:swizzle(SWAP,16)
	s_waitcnt lgkmcnt(0)
	v_add_f32_e32 v32, v32, v33
	v_mov_b32_e32 v33, v32
	s_nop 1
	v_permlane32_swap_b32_e32 v32, v33
	v_add_f32_e32 v32, v32, v33
	v_fmamk_f32 v32, v32, 0x3c000000, v205
	v_cmp_gt_f32_e32 vcc, s63, v32
	v_mul_f32_e32 v33, 0x4f800000, v32
	s_nop 0
	v_cndmask_b32_e32 v32, v32, v33, vcc
	v_sqrt_f32_e32 v33, v32
	s_nop 0
	v_add_u32_e32 v34, -1, v33
	v_fma_f32 v35, -v34, v33, v32
	v_cmp_ge_f32_e64 s[0:1], 0, v35
	v_add_u32_e32 v35, 1, v33
	s_nop 0
	v_cndmask_b32_e64 v34, v33, v34, s[0:1]
	v_fma_f32 v33, -v35, v33, v32
	v_cmp_lt_f32_e64 s[0:1], 0, v33
	s_nop 1
	v_cndmask_b32_e64 v33, v34, v35, s[0:1]
	v_mul_f32_e32 v34, 0x37800000, v33
	v_cndmask_b32_e32 v33, v33, v34, vcc
	v_cmp_class_f32_e32 vcc, v32, v206
	s_nop 1
	v_cndmask_b32_e32 v32, v33, v32, vcc
	v_rcp_f32_e32 v32, v32
	s_nop 0
	v_pk_mul_f32 v[30:31], v[30:31], v[32:33] op_sel_hi:[1,0]
	s_nop 0
	v_pk_mul_f32 v[30:31], v[0:1], v[30:31]
	s_nop 0
	v_cvt_pk_bf16_f32 v30, v30, v31
	global_store_dword v[28:29], v30, off
	s_waitcnt vmcnt(24)
	v_lshlrev_b32_e32 v28, 16, v73
	s_waitcnt vmcnt(23)
	v_lshlrev_b32_e32 v30, 16, v74
	v_and_b32_e32 v29, 0xffff0000, v73
	v_and_b32_e32 v31, 0xffff0000, v74
	v_pk_fma_f32 v[28:29], v[192:193], v[30:31], v[28:29] neg_lo:[1,0,0] neg_hi:[1,0,0]
	s_nop 0
	v_pk_mul_f32 v[30:31], v[28:29], v[28:29]
	s_nop 0
	v_add_f32_e32 v30, v30, v31
	ds_swizzle_b32 v31, v30 offset:swizzle(SWAP,1)
	s_waitcnt lgkmcnt(0)
	v_add_f32_e32 v30, v30, v31
	ds_swizzle_b32 v31, v30 offset:swizzle(SWAP,2)
	s_waitcnt lgkmcnt(0)
	v_add_f32_e32 v30, v30, v31
	ds_swizzle_b32 v31, v30 offset:swizzle(SWAP,4)
	s_waitcnt lgkmcnt(0)
	v_add_f32_e32 v30, v30, v31
	ds_swizzle_b32 v31, v30 offset:swizzle(SWAP,8)
	s_waitcnt lgkmcnt(0)
	v_add_f32_e32 v30, v30, v31
	ds_swizzle_b32 v31, v30 offset:swizzle(SWAP,16)
	s_waitcnt lgkmcnt(0)
; __device__ __forceinline__ unsigned pk2(float lo, float hi) { f32x2 v = {lo, hi}; bf16x2_hw b = __builtin_convertvector(v, bf16x2_hw); return __builtin_bit_cast(unsigned, b); }
; __device__ __forceinline__ void diffmix_block(const Grp& G, int b, int h, int qb, float lam, const float* subln, int tid) {
;     ...
;         for (int r = 0; r < 16; ++r) {
;             const float v0 = bflo(a[r]) - lam * bflo(c[r]), v1 = bfhi(a[r]) - lam * bfhi(c[r]);
;             const float ss = wave_sum(v0 * v0 + v1 * v1);
;             const float rs = 1.0f / sqrtf(ss * (1.f / 128.f) + EPSN);
;             *((unsigned*)(G.DO + (row0 + rb + r) * 1024 + h * 128) + lane) = pk2(v0 * rs * g0, v1 * rs * g1);
;         }
	v_add_f32_e32 v30, v30, v31
	v_mov_b32_e32 v31, v30
	s_nop 1
	v_permlane32_swap_b32_e32 v30, v31
	v_add_f32_e32 v30, v30, v31
	v_fmamk_f32 v30, v30, 0x3c000000, v205
	v_cmp_gt_f32_e32 vcc, s63, v30
	v_mul_f32_e32 v31, 0x4f800000, v30
	s_nop 0
	v_cndmask_b32_e32 v30, v30, v31, vcc
	v_sqrt_f32_e32 v31, v30
	s_nop 0
	v_add_u32_e32 v32, -1, v31
	v_fma_f32 v33, -v32, v31, v30
	v_cmp_ge_f32_e64 s[0:1], 0, v33
	v_add_u32_e32 v33, 1, v31
	s_nop 0
	v_cndmask_b32_e64 v32, v31, v32, s[0:1]
	v_fma_f32 v31, -v33, v31, v30
	v_cmp_lt_f32_e64 s[0:1], 0, v31
	s_nop 1
	v_cndmask_b32_e64 v31, v32, v33, s[0:1]
	v_mul_f32_e32 v32, 0x37800000, v31
	v_cndmask_b32_e32 v31, v31, v32, vcc
	v_cmp_class_f32_e32 vcc, v30, v206
	s_nop 1
	v_cndmask_b32_e32 v30, v31, v30, vcc
	v_rcp_f32_e32 v30, v30
	s_nop 0
	v_pk_mul_f32 v[28:29], v[28:29], v[30:31] op_sel_hi:[1,0]
	s_nop 0
	v_pk_mul_f32 v[28:29], v[0:1], v[28:29]
	s_nop 0
	v_cvt_pk_bf16_f32 v28, v28, v29
	global_store_dword v[26:27], v28, off
	s_waitcnt vmcnt(23)
	v_lshlrev_b32_e32 v26, 16, v75
	s_waitcnt vmcnt(22)
	v_lshlrev_b32_e32 v28, 16, v76
	v_and_b32_e32 v27, 0xffff0000, v75
	v_and_b32_e32 v29, 0xffff0000, v76
	v_pk_fma_f32 v[26:27], v[192:193], v[28:29], v[26:27] neg_lo:[1,0,0] neg_hi:[1,0,0]
	s_nop 0
	v_pk_mul_f32 v[28:29], v[26:27], v[26:27]
	s_nop 0
	v_add_f32_e32 v28, v28, v29
	ds_swizzle_b32 v29, v28 offset:swizzle(SWAP,1)
	s_waitcnt lgkmcnt(0)
	v_add_f32_e32 v28, v28, v29
	ds_swizzle_b32 v29, v28 offset:swizzle(SWAP,2)
	s_waitcnt lgkmcnt(0)
	v_add_f32_e32 v28, v28, v29
	ds_swizzle_b32 v29, v28 offset:swizzle(SWAP,4)
	s_waitcnt lgkmcnt(0)
	v_add_f32_e32 v28, v28, v29
	ds_swizzle_b32 v29, v28 offset:swizzle(SWAP,8)
	s_waitcnt lgkmcnt(0)
	v_add_f32_e32 v28, v28, v29
	ds_swizzle_b32 v29, v28 offset:swizzle(SWAP,16)
	s_waitcnt lgkmcnt(0)
	v_add_f32_e32 v28, v28, v29
	v_mov_b32_e32 v29, v28
	s_nop 1
	v_permlane32_swap_b32_e32 v28, v29
	v_add_f32_e32 v28, v28, v29
	v_fmamk_f32 v28, v28, 0x3c000000, v205
	v_cmp_gt_f32_e32 vcc, s63, v28
	v_mul_f32_e32 v29, 0x4f800000, v28
	s_nop 0
	v_cndmask_b32_e32 v28, v28, v29, vcc
	v_sqrt_f32_e32 v29, v28
	s_nop 0
	v_add_u32_e32 v30, -1, v29
	v_fma_f32 v31, -v30, v29, v28
	v_cmp_ge_f32_e64 s[0:1], 0, v31
	v_add_u32_e32 v31, 1, v29
	s_nop 0
	v_cndmask_b32_e64 v30, v29, v30, s[0:1]
	v_fma_f32 v29, -v31, v29, v28
	v_cmp_lt_f32_e64 s[0:1], 0, v29
	s_nop 1
	v_cndmask_b32_e64 v29, v30, v31, s[0:1]
	v_mul_f32_e32 v30, 0x37800000, v29
	v_cndmask_b32_e32 v29, v29, v30, vcc
	v_cmp_class_f32_e32 vcc, v28, v206
	s_nop 1
	v_cndmask_b32_e32 v28, v29, v28, vcc
	v_rcp_f32_e32 v28, v28
	s_nop 0
	v_pk_mul_f32 v[26:27], v[26:27], v[28:29] op_sel_hi:[1,0]
	s_nop 0
	v_pk_mul_f32 v[26:27], v[0:1], v[26:27]
	s_nop 0
	v_cvt_pk_bf16_f32 v26, v26, v27
	global_store_dword v[24:25], v26, off
	s_waitcnt vmcnt(22)
	v_lshlrev_b32_e32 v24, 16, v48
	s_waitcnt vmcnt(21)
	v_lshlrev_b32_e32 v26, 16, v49
	v_and_b32_e32 v25, 0xffff0000, v48
	v_and_b32_e32 v27, 0xffff0000, v49
	v_pk_fma_f32 v[24:25], v[192:193], v[26:27], v[24:25] neg_lo:[1,0,0] neg_hi:[1,0,0]
	s_nop 0
	v_pk_mul_f32 v[26:27], v[24:25], v[24:25]
	s_nop 0
	v_add_f32_e32 v26, v26, v27
	ds_swizzle_b32 v27, v26 offset:swizzle(SWAP,1)
	s_waitcnt lgkmcnt(0)
	v_add_f32_e32 v26, v26, v27
	ds_swizzle_b32 v27, v26 offset:swizzle(SWAP,2)
	s_waitcnt lgkmcnt(0)
	v_add_f32_e32 v26, v26, v27
	ds_swizzle_b32 v27, v26 offset:swizzle(SWAP,4)
	s_waitcnt lgkmcnt(0)
	v_add_f32_e32 v26, v26, v27
	ds_swizzle_b32 v27, v26 offset:swizzle(SWAP,8)
	s_waitcnt lgkmcnt(0)
	v_add_f32_e32 v26, v26, v27
	ds_swizzle_b32 v27, v26 offset:swizzle(SWAP,16)
	s_waitcnt lgkmcnt(0)
	v_add_f32_e32 v26, v26, v27
	v_mov_b32_e32 v27, v26
	s_nop 1
	v_permlane32_swap_b32_e32 v26, v27
	v_add_f32_e32 v26, v26, v27
	v_fmamk_f32 v26, v26, 0x3c000000, v205
	v_cmp_gt_f32_e32 vcc, s63, v26
	v_mul_f32_e32 v27, 0x4f800000, v26
	s_nop 0
	v_cndmask_b32_e32 v26, v26, v27, vcc
	v_sqrt_f32_e32 v27, v26
	s_nop 0
	v_add_u32_e32 v28, -1, v27
	v_fma_f32 v29, -v28, v27, v26
	v_cmp_ge_f32_e64 s[0:1], 0, v29
	v_add_u32_e32 v29, 1, v27
	s_nop 0
	v_cndmask_b32_e64 v28, v27, v28, s[0:1]
	v_fma_f32 v27, -v29, v27, v26
	v_cmp_lt_f32_e64 s[0:1], 0, v27
	s_nop 1
	v_cndmask_b32_e64 v27, v28, v29, s[0:1]
	v_mul_f32_e32 v28, 0x37800000, v27
	v_cndmask_b32_e32 v27, v27, v28, vcc
	v_cmp_class_f32_e32 vcc, v26, v206
	s_nop 1
	v_cndmask_b32_e32 v26, v27, v26, vcc
	v_rcp_f32_e32 v26, v26
	s_nop 0
	v_pk_mul_f32 v[24:25], v[24:25], v[26:27] op_sel_hi:[1,0]
	s_nop 0
	v_pk_mul_f32 v[24:25], v[0:1], v[24:25]
	s_nop 0
	v_cvt_pk_bf16_f32 v24, v24, v25
	global_store_dword v[22:23], v24, off
	s_waitcnt vmcnt(21)
	v_lshlrev_b32_e32 v22, 16, v46
	s_waitcnt vmcnt(20)
	v_lshlrev_b32_e32 v24, 16, v47
	v_and_b32_e32 v23, 0xffff0000, v46
	v_and_b32_e32 v25, 0xffff0000, v47
	v_pk_fma_f32 v[22:23], v[192:193], v[24:25], v[22:23] neg_lo:[1,0,0] neg_hi:[1,0,0]
	s_nop 0
	v_pk_mul_f32 v[24:25], v[22:23], v[22:23]
	s_nop 0
	v_add_f32_e32 v24, v24, v25
	ds_swizzle_b32 v25, v24 offset:swizzle(SWAP,1)
	s_waitcnt lgkmcnt(0)
	v_add_f32_e32 v24, v24, v25
	ds_swizzle_b32 v25, v24 offset:swizzle(SWAP,2)
	s_waitcnt lgkmcnt(0)
	v_add_f32_e32 v24, v24, v25
	ds_swizzle_b32 v25, v24 offset:swizzle(SWAP,4)
	s_waitcnt lgkmcnt(0)
	v_add_f32_e32 v24, v24, v25
	ds_swizzle_b32 v25, v24 offset:swizzle(SWAP,8)
	s_waitcnt lgkmcnt(0)
	v_add_f32_e32 v24, v24, v25
	ds_swizzle_b32 v25, v24 offset:swizzle(SWAP,16)
	s_waitcnt lgkmcnt(0)
; __device__ __forceinline__ unsigned pk2(float lo, float hi) { f32x2 v = {lo, hi}; bf16x2_hw b = __builtin_convertvector(v, bf16x2_hw); return __builtin_bit_cast(unsigned, b); }
; __device__ __forceinline__ void diffmix_block(const Grp& G, int b, int h, int qb, float lam, const float* subln, int tid) {
;     ...
;         for (int r = 0; r < 16; ++r) {
;             const float v0 = bflo(a[r]) - lam * bflo(c[r]), v1 = bfhi(a[r]) - lam * bfhi(c[r]);
;             const float ss = wave_sum(v0 * v0 + v1 * v1);
;             const float rs = 1.0f / sqrtf(ss * (1.f / 128.f) + EPSN);
;             *((unsigned*)(G.DO + (row0 + rb + r) * 1024 + h * 128) + lane) = pk2(v0 * rs * g0, v1 * rs * g1);
;         }
	v_add_f32_e32 v24, v24, v25
	v_mov_b32_e32 v25, v24
	s_nop 1
	v_permlane32_swap_b32_e32 v24, v25
	v_add_f32_e32 v24, v24, v25
	v_fmamk_f32 v24, v24, 0x3c000000, v205
	v_cmp_gt_f32_e32 vcc, s63, v24
	v_mul_f32_e32 v25, 0x4f800000, v24
	s_nop 0
	v_cndmask_b32_e32 v24, v24, v25, vcc
	v_sqrt_f32_e32 v25, v24
	s_nop 0
	v_add_u32_e32 v26, -1, v25
	v_fma_f32 v27, -v26, v25, v24
	v_cmp_ge_f32_e64 s[0:1], 0, v27
	v_add_u32_e32 v27, 1, v25
	s_nop 0
	v_cndmask_b32_e64 v26, v25, v26, s[0:1]
	v_fma_f32 v25, -v27, v25, v24
	v_cmp_lt_f32_e64 s[0:1], 0, v25
	s_nop 1
	v_cndmask_b32_e64 v25, v26, v27, s[0:1]
	v_mul_f32_e32 v26, 0x37800000, v25
	v_cndmask_b32_e32 v25, v25, v26, vcc
	v_cmp_class_f32_e32 vcc, v24, v206
	s_nop 1
	v_cndmask_b32_e32 v24, v25, v24, vcc
	v_rcp_f32_e32 v24, v24
	s_nop 0
	v_pk_mul_f32 v[22:23], v[22:23], v[24:25] op_sel_hi:[1,0]
	s_nop 0
	v_pk_mul_f32 v[22:23], v[0:1], v[22:23]
	s_nop 0
	v_cvt_pk_bf16_f32 v22, v22, v23
	global_store_dword v[20:21], v22, off
	s_waitcnt vmcnt(20)
	v_lshlrev_b32_e32 v20, 16, v44
	s_waitcnt vmcnt(19)
	v_lshlrev_b32_e32 v22, 16, v45
	v_and_b32_e32 v21, 0xffff0000, v44
	v_and_b32_e32 v23, 0xffff0000, v45
	v_pk_fma_f32 v[20:21], v[192:193], v[22:23], v[20:21] neg_lo:[1,0,0] neg_hi:[1,0,0]
	s_nop 0
	v_pk_mul_f32 v[22:23], v[20:21], v[20:21]
	s_nop 0
	v_add_f32_e32 v22, v22, v23
	ds_swizzle_b32 v23, v22 offset:swizzle(SWAP,1)
	s_waitcnt lgkmcnt(0)
	v_add_f32_e32 v22, v22, v23
	ds_swizzle_b32 v23, v22 offset:swizzle(SWAP,2)
	s_waitcnt lgkmcnt(0)
	v_add_f32_e32 v22, v22, v23
	ds_swizzle_b32 v23, v22 offset:swizzle(SWAP,4)
	s_waitcnt lgkmcnt(0)
	v_add_f32_e32 v22, v22, v23
	ds_swizzle_b32 v23, v22 offset:swizzle(SWAP,8)
	s_waitcnt lgkmcnt(0)
	v_add_f32_e32 v22, v22, v23
	ds_swizzle_b32 v23, v22 offset:swizzle(SWAP,16)
	s_waitcnt lgkmcnt(0)
	v_add_f32_e32 v22, v22, v23
	v_mov_b32_e32 v23, v22
	s_nop 1
	v_permlane32_swap_b32_e32 v22, v23
	v_add_f32_e32 v22, v22, v23
	v_fmamk_f32 v22, v22, 0x3c000000, v205
	v_cmp_gt_f32_e32 vcc, s63, v22
	v_mul_f32_e32 v23, 0x4f800000, v22
	s_nop 0
	v_cndmask_b32_e32 v22, v22, v23, vcc
	v_sqrt_f32_e32 v23, v22
	s_nop 0
	v_add_u32_e32 v24, -1, v23
	v_fma_f32 v25, -v24, v23, v22
	v_cmp_ge_f32_e64 s[0:1], 0, v25
	v_add_u32_e32 v25, 1, v23
	s_nop 0
	v_cndmask_b32_e64 v24, v23, v24, s[0:1]
	v_fma_f32 v23, -v25, v23, v22
	v_cmp_lt_f32_e64 s[0:1], 0, v23
	s_nop 1
	v_cndmask_b32_e64 v23, v24, v25, s[0:1]
	v_mul_f32_e32 v24, 0x37800000, v23
	v_cndmask_b32_e32 v23, v23, v24, vcc
	v_cmp_class_f32_e32 vcc, v22, v206
	s_nop 1
	v_cndmask_b32_e32 v22, v23, v22, vcc
	v_rcp_f32_e32 v22, v22
	s_nop 0
	v_pk_mul_f32 v[20:21], v[20:21], v[22:23] op_sel_hi:[1,0]
	s_nop 0
	v_pk_mul_f32 v[20:21], v[0:1], v[20:21]
	s_nop 0
	v_cvt_pk_bf16_f32 v20, v20, v21
	global_store_dword v[18:19], v20, off
	s_waitcnt vmcnt(19)
	v_lshlrev_b32_e32 v18, 16, v42
	s_waitcnt vmcnt(18)
	v_lshlrev_b32_e32 v20, 16, v43
	v_and_b32_e32 v19, 0xffff0000, v42
	v_and_b32_e32 v21, 0xffff0000, v43
	v_pk_fma_f32 v[18:19], v[192:193], v[20:21], v[18:19] neg_lo:[1,0,0] neg_hi:[1,0,0]
	s_nop 0
	v_pk_mul_f32 v[20:21], v[18:19], v[18:19]
	s_nop 0
	v_add_f32_e32 v20, v20, v21
	ds_swizzle_b32 v21, v20 offset:swizzle(SWAP,1)
	s_waitcnt lgkmcnt(0)
	v_add_f32_e32 v20, v20, v21
	ds_swizzle_b32 v21, v20 offset:swizzle(SWAP,2)
	s_waitcnt lgkmcnt(0)
	v_add_f32_e32 v20, v20, v21
	ds_swizzle_b32 v21, v20 offset:swizzle(SWAP,4)
	s_waitcnt lgkmcnt(0)
	v_add_f32_e32 v20, v20, v21
	ds_swizzle_b32 v21, v20 offset:swizzle(SWAP,8)
	s_waitcnt lgkmcnt(0)
	v_add_f32_e32 v20, v20, v21
	ds_swizzle_b32 v21, v20 offset:swizzle(SWAP,16)
	s_waitcnt lgkmcnt(0)
	v_add_f32_e32 v20, v20, v21
	v_mov_b32_e32 v21, v20
	s_nop 1
	v_permlane32_swap_b32_e32 v20, v21
	v_add_f32_e32 v20, v20, v21
	v_fmamk_f32 v20, v20, 0x3c000000, v205
	v_cmp_gt_f32_e32 vcc, s63, v20
	v_mul_f32_e32 v21, 0x4f800000, v20
	s_nop 0
	v_cndmask_b32_e32 v20, v20, v21, vcc
	v_sqrt_f32_e32 v21, v20
	s_nop 0
	v_add_u32_e32 v22, -1, v21
	v_fma_f32 v23, -v22, v21, v20
	v_cmp_ge_f32_e64 s[0:1], 0, v23
	v_add_u32_e32 v23, 1, v21
	s_nop 0
	v_cndmask_b32_e64 v22, v21, v22, s[0:1]
	v_fma_f32 v21, -v23, v21, v20
	v_cmp_lt_f32_e64 s[0:1], 0, v21
	s_nop 1
	v_cndmask_b32_e64 v21, v22, v23, s[0:1]
	v_mul_f32_e32 v22, 0x37800000, v21
	v_cndmask_b32_e32 v21, v21, v22, vcc
	v_cmp_class_f32_e32 vcc, v20, v206
	s_nop 1
	v_cndmask_b32_e32 v20, v21, v20, vcc
	v_rcp_f32_e32 v20, v20
	s_nop 0
	v_pk_mul_f32 v[18:19], v[18:19], v[20:21] op_sel_hi:[1,0]
	s_nop 0
	v_pk_mul_f32 v[18:19], v[0:1], v[18:19]
	s_nop 0
	v_cvt_pk_bf16_f32 v18, v18, v19
	global_store_dword v[16:17], v18, off
	s_waitcnt vmcnt(18)
	v_lshlrev_b32_e32 v16, 16, v40
	s_waitcnt vmcnt(17)
	v_lshlrev_b32_e32 v18, 16, v41
	v_and_b32_e32 v17, 0xffff0000, v40
	v_and_b32_e32 v19, 0xffff0000, v41
	v_pk_fma_f32 v[16:17], v[192:193], v[18:19], v[16:17] neg_lo:[1,0,0] neg_hi:[1,0,0]
	s_nop 0
	v_pk_mul_f32 v[18:19], v[16:17], v[16:17]
	s_nop 0
	v_add_f32_e32 v18, v18, v19
	ds_swizzle_b32 v19, v18 offset:swizzle(SWAP,1)
	s_waitcnt lgkmcnt(0)
	v_add_f32_e32 v18, v18, v19
	ds_swizzle_b32 v19, v18 offset:swizzle(SWAP,2)
	s_waitcnt lgkmcnt(0)
	v_add_f32_e32 v18, v18, v19
	ds_swizzle_b32 v19, v18 offset:swizzle(SWAP,4)
	s_waitcnt lgkmcnt(0)
	v_add_f32_e32 v18, v18, v19
	ds_swizzle_b32 v19, v18 offset:swizzle(SWAP,8)
	s_waitcnt lgkmcnt(0)
	v_add_f32_e32 v18, v18, v19
	ds_swizzle_b32 v19, v18 offset:swizzle(SWAP,16)
	s_waitcnt lgkmcnt(0)
; __device__ __forceinline__ unsigned pk2(float lo, float hi) { f32x2 v = {lo, hi}; bf16x2_hw b = __builtin_convertvector(v, bf16x2_hw); return __builtin_bit_cast(unsigned, b); }
; __device__ __forceinline__ void diffmix_block(const Grp& G, int b, int h, int qb, float lam, const float* subln, int tid) {
;     ...
;         for (int r = 0; r < 16; ++r) {
;             const float v0 = bflo(a[r]) - lam * bflo(c[r]), v1 = bfhi(a[r]) - lam * bfhi(c[r]);
;             const float ss = wave_sum(v0 * v0 + v1 * v1);
;             const float rs = 1.0f / sqrtf(ss * (1.f / 128.f) + EPSN);
;             *((unsigned*)(G.DO + (row0 + rb + r) * 1024 + h * 128) + lane) = pk2(v0 * rs * g0, v1 * rs * g1);
;         }
	v_add_f32_e32 v18, v18, v19
	v_mov_b32_e32 v19, v18
	s_nop 1
	v_permlane32_swap_b32_e32 v18, v19
	v_add_f32_e32 v18, v18, v19
	v_fmamk_f32 v18, v18, 0x3c000000, v205
	v_cmp_gt_f32_e32 vcc, s63, v18
	v_mul_f32_e32 v19, 0x4f800000, v18
	s_nop 0
	v_cndmask_b32_e32 v18, v18, v19, vcc
	v_sqrt_f32_e32 v19, v18
	s_nop 0
	v_add_u32_e32 v20, -1, v19
	v_fma_f32 v21, -v20, v19, v18
	v_cmp_ge_f32_e64 s[0:1], 0, v21
	v_add_u32_e32 v21, 1, v19
	s_nop 0
	v_cndmask_b32_e64 v20, v19, v20, s[0:1]
	v_fma_f32 v19, -v21, v19, v18
	v_cmp_lt_f32_e64 s[0:1], 0, v19
	s_nop 1
	v_cndmask_b32_e64 v19, v20, v21, s[0:1]
	v_mul_f32_e32 v20, 0x37800000, v19
	v_cndmask_b32_e32 v19, v19, v20, vcc
	v_cmp_class_f32_e32 vcc, v18, v206
	s_nop 1
	v_cndmask_b32_e32 v18, v19, v18, vcc
	v_rcp_f32_e32 v18, v18
	s_nop 0
	v_pk_mul_f32 v[16:17], v[16:17], v[18:19] op_sel_hi:[1,0]
	s_nop 0
	v_pk_mul_f32 v[16:17], v[0:1], v[16:17]
	s_nop 0
	v_cvt_pk_bf16_f32 v16, v16, v17
	global_store_dword v[14:15], v16, off
	s_waitcnt vmcnt(17)
	v_lshlrev_b32_e32 v14, 16, v38
	s_waitcnt vmcnt(16)
	v_lshlrev_b32_e32 v16, 16, v39
	v_and_b32_e32 v15, 0xffff0000, v38
	v_and_b32_e32 v17, 0xffff0000, v39
	v_pk_fma_f32 v[14:15], v[192:193], v[16:17], v[14:15] neg_lo:[1,0,0] neg_hi:[1,0,0]
	s_nop 0
	v_pk_mul_f32 v[16:17], v[14:15], v[14:15]
	s_nop 0
	v_add_f32_e32 v16, v16, v17
	ds_swizzle_b32 v17, v16 offset:swizzle(SWAP,1)
	s_waitcnt lgkmcnt(0)
	v_add_f32_e32 v16, v16, v17
	ds_swizzle_b32 v17, v16 offset:swizzle(SWAP,2)
	s_waitcnt lgkmcnt(0)
	v_add_f32_e32 v16, v16, v17
	ds_swizzle_b32 v17, v16 offset:swizzle(SWAP,4)
	s_waitcnt lgkmcnt(0)
	v_add_f32_e32 v16, v16, v17
	ds_swizzle_b32 v17, v16 offset:swizzle(SWAP,8)
	s_waitcnt lgkmcnt(0)
	v_add_f32_e32 v16, v16, v17
	ds_swizzle_b32 v17, v16 offset:swizzle(SWAP,16)
	s_waitcnt lgkmcnt(0)
	v_add_f32_e32 v16, v16, v17
	v_mov_b32_e32 v17, v16
	s_nop 1
	v_permlane32_swap_b32_e32 v16, v17
	v_add_f32_e32 v16, v16, v17
	v_fmamk_f32 v16, v16, 0x3c000000, v205
	v_cmp_gt_f32_e32 vcc, s63, v16
	v_mul_f32_e32 v17, 0x4f800000, v16
	s_nop 0
	v_cndmask_b32_e32 v16, v16, v17, vcc
	v_sqrt_f32_e32 v17, v16
	s_nop 0
	v_add_u32_e32 v18, -1, v17
	v_fma_f32 v19, -v18, v17, v16
	v_cmp_ge_f32_e64 s[0:1], 0, v19
	v_add_u32_e32 v19, 1, v17
	s_nop 0
	v_cndmask_b32_e64 v18, v17, v18, s[0:1]
	v_fma_f32 v17, -v19, v17, v16
	v_cmp_lt_f32_e64 s[0:1], 0, v17
	s_nop 1
	v_cndmask_b32_e64 v17, v18, v19, s[0:1]
	v_mul_f32_e32 v18, 0x37800000, v17
	v_cndmask_b32_e32 v17, v17, v18, vcc
	v_cmp_class_f32_e32 vcc, v16, v206
	s_nop 1
	v_cndmask_b32_e32 v16, v17, v16, vcc
	v_rcp_f32_e32 v16, v16
	s_nop 0
	v_pk_mul_f32 v[14:15], v[14:15], v[16:17] op_sel_hi:[1,0]
	s_nop 0
	v_pk_mul_f32 v[14:15], v[0:1], v[14:15]
	s_nop 0
	v_cvt_pk_bf16_f32 v14, v14, v15
	global_store_dword v[12:13], v14, off
	s_waitcnt vmcnt(16)
	v_lshlrev_b32_e32 v12, 16, v36
	s_waitcnt vmcnt(15)
	v_lshlrev_b32_e32 v14, 16, v37
	v_and_b32_e32 v13, 0xffff0000, v36
	v_and_b32_e32 v15, 0xffff0000, v37
	v_pk_fma_f32 v[12:13], v[192:193], v[14:15], v[12:13] neg_lo:[1,0,0] neg_hi:[1,0,0]
	s_nop 0
	v_pk_mul_f32 v[14:15], v[12:13], v[12:13]
	s_nop 0
	v_add_f32_e32 v14, v14, v15
	ds_swizzle_b32 v15, v14 offset:swizzle(SWAP,1)
	s_waitcnt lgkmcnt(0)
	v_add_f32_e32 v14, v14, v15
	ds_swizzle_b32 v15, v14 offset:swizzle(SWAP,2)
	s_waitcnt lgkmcnt(0)
	v_add_f32_e32 v14, v14, v15
	ds_swizzle_b32 v15, v14 offset:swizzle(SWAP,4)
	s_waitcnt lgkmcnt(0)
	v_add_f32_e32 v14, v14, v15
	ds_swizzle_b32 v15, v14 offset:swizzle(SWAP,8)
	s_waitcnt lgkmcnt(0)
	v_add_f32_e32 v14, v14, v15
	ds_swizzle_b32 v15, v14 offset:swizzle(SWAP,16)
	s_waitcnt lgkmcnt(0)
	v_add_f32_e32 v14, v14, v15
	v_mov_b32_e32 v15, v14
	s_nop 1
	v_permlane32_swap_b32_e32 v14, v15
	v_add_f32_e32 v14, v14, v15
	v_fmamk_f32 v14, v14, 0x3c000000, v205
	v_cmp_gt_f32_e32 vcc, s63, v14
	v_mul_f32_e32 v15, 0x4f800000, v14
	s_nop 0
	v_cndmask_b32_e32 v14, v14, v15, vcc
	v_sqrt_f32_e32 v15, v14
	s_nop 0
	v_add_u32_e32 v16, -1, v15
	v_fma_f32 v17, -v16, v15, v14
	v_cmp_ge_f32_e64 s[0:1], 0, v17
	v_add_u32_e32 v17, 1, v15
	s_nop 0
	v_cndmask_b32_e64 v16, v15, v16, s[0:1]
	v_fma_f32 v15, -v17, v15, v14
	v_cmp_lt_f32_e64 s[0:1], 0, v15
	s_nop 1
	v_cndmask_b32_e64 v15, v16, v17, s[0:1]
	v_mul_f32_e32 v16, 0x37800000, v15
	v_cndmask_b32_e32 v15, v15, v16, vcc
	v_cmp_class_f32_e32 vcc, v14, v206
	s_nop 1
	v_cndmask_b32_e32 v14, v15, v14, vcc
	s_mov_b64 s[0:1], 16
	v_rcp_f32_e32 v14, v14
	s_nop 0
	v_pk_mul_f32 v[12:13], v[12:13], v[14:15] op_sel_hi:[1,0]
	s_and_b64 vcc, exec, s[2:3]
	v_pk_mul_f32 v[12:13], v[0:1], v[12:13]
	s_mov_b64 s[2:3], 0
	v_cvt_pk_bf16_f32 v12, v12, v13
	global_store_dword v[10:11], v12, off
	s_cbranch_vccnz .LBB0_555
	s_or_b64 s[0:1], s[24:25], s[4:5]
	v_lshl_add_u64 v[6:7], s[0:1], 0, v[6:7]
	s_mov_b64 s[0:1], 0
	s_mov_b64 s[2:3], -1
; __device__ __forceinline__ unsigned pk2(float lo, float hi) { f32x2 v = {lo, hi}; bf16x2_hw b = __builtin_convertvector(v, bf16x2_hw); return __builtin_bit_cast(unsigned, b); }
; __device__ __forceinline__ void diffmix_block(const Grp& G, int b, int h, int qb, float lam, const float* subln, int tid) {
;     const int lane = tid & 63, wid = tid >> 6;
;     const float g0 = subln[2 * lane] * 0.8f, g1 = subln[2 * lane + 1] * 0.8f;
;     const size_t row0 = (size_t)b * TS + qb * 256 + wid * 32;
; #pragma unroll 1
;     for (int rb = 0; rb < 32; rb += 16) {
;         unsigned a[16], c[16];
; #pragma unroll
;         for (int r = 0; r < 16; ++r) { a[r] = *((const unsigned*)(G.DO + (row0 + rb + r) * 1024 + h * 128) + lane); c[r] = *((const unsigned*)(G.XN + (row0 + rb + r) * 1024 + h * 128) + lane); }
; #pragma unroll
;         for (int r = 0; r < 16; ++r) {
;             const float v0 = bflo(a[r]) - lam * bflo(c[r]), v1 = bfhi(a[r]) - lam * bfhi(c[r]);
;             const float ss = wave_sum(v0 * v0 + v1 * v1);
;             const float rs = 1.0f / sqrtf(ss * (1.f / 128.f) + EPSN);
;             *((unsigned*)(G.DO + (row0 + rb + r) * 1024 + h * 128) + lane) = pk2(v0 * rs * g0, v1 * rs * g1);
;         }
;     }
; }
.LBB0_557:
	v_or_b32_e32 v9, s1, v7
	v_or_b32_e32 v8, s0, v6
	v_lshlrev_b64 v[48:49], 11, v[8:9]
	v_lshl_add_u64 v[50:51], v[2:3], 0, v[48:49]
	v_lshl_add_u64 v[8:9], v[4:5], 0, v[48:49]
	global_load_dword v57, v[50:51], off
	global_load_dword v58, v[8:9], off
	v_or_b32_e32 v8, 0x800, v48
	v_mov_b32_e32 v9, v49
	v_lshl_add_u64 v[52:53], v[2:3], 0, v[8:9]
	v_lshl_add_u64 v[8:9], v[4:5], 0, v[8:9]
	global_load_dword v59, v[52:53], off
	global_load_dword v60, v[8:9], off
	v_or_b32_e32 v8, 0x1000, v48
	v_mov_b32_e32 v9, v49
	v_lshl_add_u64 v[54:55], v[2:3], 0, v[8:9]
	v_lshl_add_u64 v[8:9], v[4:5], 0, v[8:9]
	global_load_dword v61, v[54:55], off
	global_load_dword v62, v[8:9], off
	v_or_b32_e32 v8, 0x1800, v48
	v_mov_b32_e32 v9, v49
	v_lshl_add_u64 v[32:33], v[2:3], 0, v[8:9]
	v_lshl_add_u64 v[8:9], v[4:5], 0, v[8:9]
	global_load_dword v63, v[32:33], off
	global_load_dword v64, v[8:9], off
	v_or_b32_e32 v8, 0x2000, v48
	v_mov_b32_e32 v9, v49
	v_lshl_add_u64 v[30:31], v[2:3], 0, v[8:9]
	v_lshl_add_u64 v[8:9], v[4:5], 0, v[8:9]
	global_load_dword v65, v[30:31], off
	global_load_dword v66, v[8:9], off
	v_or_b32_e32 v8, 0x2800, v48
	v_mov_b32_e32 v9, v49
	v_lshl_add_u64 v[28:29], v[2:3], 0, v[8:9]
	v_lshl_add_u64 v[8:9], v[4:5], 0, v[8:9]
	global_load_dword v67, v[28:29], off
	global_load_dword v68, v[8:9], off
	v_or_b32_e32 v8, 0x3000, v48
	v_mov_b32_e32 v9, v49
	v_lshl_add_u64 v[26:27], v[2:3], 0, v[8:9]
	v_lshl_add_u64 v[8:9], v[4:5], 0, v[8:9]
	global_load_dword v69, v[26:27], off
	global_load_dword v70, v[8:9], off
	v_or_b32_e32 v8, 0x3800, v48
	v_mov_b32_e32 v9, v49
	v_lshl_add_u64 v[24:25], v[2:3], 0, v[8:9]
	v_lshl_add_u64 v[8:9], v[4:5], 0, v[8:9]
	global_load_dword v71, v[24:25], off
	global_load_dword v72, v[8:9], off
	v_or_b32_e32 v8, 0x4000, v48
	v_mov_b32_e32 v9, v49
	v_lshl_add_u64 v[22:23], v[2:3], 0, v[8:9]
	v_lshl_add_u64 v[8:9], v[4:5], 0, v[8:9]
	global_load_dword v73, v[22:23], off
	global_load_dword v74, v[8:9], off
	v_or_b32_e32 v8, 0x4800, v48
	v_mov_b32_e32 v9, v49
	v_lshl_add_u64 v[20:21], v[2:3], 0, v[8:9]
	v_lshl_add_u64 v[8:9], v[4:5], 0, v[8:9]
	global_load_dword v46, v[20:21], off
	global_load_dword v47, v[8:9], off
	v_or_b32_e32 v8, 0x5000, v48
	v_mov_b32_e32 v9, v49
	v_lshl_add_u64 v[18:19], v[2:3], 0, v[8:9]
	v_lshl_add_u64 v[8:9], v[4:5], 0, v[8:9]
	global_load_dword v44, v[18:19], off
	global_load_dword v45, v[8:9], off
	v_or_b32_e32 v8, 0x5800, v48
	v_mov_b32_e32 v9, v49
	v_lshl_add_u64 v[16:17], v[2:3], 0, v[8:9]
	v_lshl_add_u64 v[8:9], v[4:5], 0, v[8:9]
	global_load_dword v42, v[16:17], off
	global_load_dword v43, v[8:9], off
	v_or_b32_e32 v8, 0x6000, v48
	v_mov_b32_e32 v9, v49
	v_lshl_add_u64 v[14:15], v[2:3], 0, v[8:9]
	v_lshl_add_u64 v[8:9], v[4:5], 0, v[8:9]
	global_load_dword v40, v[14:15], off
	global_load_dword v41, v[8:9], off
	v_or_b32_e32 v8, 0x6800, v48
	v_mov_b32_e32 v9, v49
	v_lshl_add_u64 v[12:13], v[2:3], 0, v[8:9]
	v_lshl_add_u64 v[8:9], v[4:5], 0, v[8:9]
	global_load_dword v38, v[12:13], off
	global_load_dword v39, v[8:9], off
	v_or_b32_e32 v8, 0x7000, v48
	v_mov_b32_e32 v9, v49
	v_lshl_add_u64 v[10:11], v[2:3], 0, v[8:9]
	v_lshl_add_u64 v[8:9], v[4:5], 0, v[8:9]
	v_or_b32_e32 v48, 0x7800, v48
	global_load_dword v36, v[10:11], off
	global_load_dword v37, v[8:9], off
	v_lshl_add_u64 v[8:9], v[2:3], 0, v[48:49]
	v_lshl_add_u64 v[48:49], v[4:5], 0, v[48:49]
	global_load_dword v34, v[8:9], off
	global_load_dword v35, v[48:49], off
	s_waitcnt vmcnt(31)
	v_lshlrev_b32_e32 v48, 16, v57
	s_waitcnt vmcnt(30)
	v_lshlrev_b32_e32 v56, 16, v58
	v_and_b32_e32 v49, 0xffff0000, v57
	v_and_b32_e32 v57, 0xffff0000, v58
	v_pk_fma_f32 v[48:49], v[192:193], v[56:57], v[48:49] neg_lo:[1,0,0] neg_hi:[1,0,0]
	s_nop 0
	v_pk_mul_f32 v[56:57], v[48:49], v[48:49]
	s_nop 0
	v_add_f32_e32 v56, v56, v57
	ds_swizzle_b32 v57, v56 offset:swizzle(SWAP,1)
	s_waitcnt lgkmcnt(0)
	v_add_f32_e32 v56, v56, v57
	ds_swizzle_b32 v57, v56 offset:swizzle(SWAP,2)
	s_waitcnt lgkmcnt(0)
	v_add_f32_e32 v56, v56, v57
	ds_swizzle_b32 v57, v56 offset:swizzle(SWAP,4)
	s_waitcnt lgkmcnt(0)
	v_add_f32_e32 v56, v56, v57
	ds_swizzle_b32 v57, v56 offset:swizzle(SWAP,8)
	s_waitcnt lgkmcnt(0)
	v_add_f32_e32 v56, v56, v57
	ds_swizzle_b32 v57, v56 offset:swizzle(SWAP,16)
	s_waitcnt lgkmcnt(0)
	v_add_f32_e32 v56, v56, v57
	v_mov_b32_e32 v57, v56
	s_nop 1
	v_permlane32_swap_b32_e32 v56, v57
	v_add_f32_e32 v56, v56, v57
	v_fmamk_f32 v56, v56, 0x3c000000, v205
	v_cmp_gt_f32_e32 vcc, s63, v56
	v_mul_f32_e32 v57, 0x4f800000, v56
	s_nop 0
	v_cndmask_b32_e32 v56, v56, v57, vcc
	v_sqrt_f32_e32 v57, v56
	s_nop 0
	v_add_u32_e32 v58, -1, v57
	v_fma_f32 v75, -v58, v57, v56
	v_cmp_ge_f32_e64 s[0:1], 0, v75
	v_add_u32_e32 v75, 1, v57
	s_nop 0
	v_cndmask_b32_e64 v58, v57, v58, s[0:1]
	v_fma_f32 v57, -v75, v57, v56
	v_cmp_lt_f32_e64 s[0:1], 0, v57
	s_nop 1
	v_cndmask_b32_e64 v57, v58, v75, s[0:1]
	v_mul_f32_e32 v58, 0x37800000, v57
	v_cndmask_b32_e32 v57, v57, v58, vcc
	v_cmp_class_f32_e32 vcc, v56, v206
	s_nop 1
	v_cndmask_b32_e32 v56, v57, v56, vcc
	v_rcp_f32_e32 v56, v56
	s_nop 0
	v_pk_mul_f32 v[48:49], v[48:49], v[56:57] op_sel_hi:[1,0]
	s_nop 0
	v_pk_mul_f32 v[48:49], v[0:1], v[48:49]
	s_nop 0
	v_cvt_pk_bf16_f32 v48, v48, v49
	global_store_dword v[50:51], v48, off
	s_waitcnt vmcnt(30)
	v_lshlrev_b32_e32 v48, 16, v59
	s_waitcnt vmcnt(29)
	v_lshlrev_b32_e32 v50, 16, v60
	v_and_b32_e32 v49, 0xffff0000, v59
	v_and_b32_e32 v51, 0xffff0000, v60
	v_pk_fma_f32 v[48:49], v[192:193], v[50:51], v[48:49] neg_lo:[1,0,0] neg_hi:[1,0,0]
	s_nop 0
	v_pk_mul_f32 v[50:51], v[48:49], v[48:49]
	s_nop 0
	v_add_f32_e32 v50, v50, v51
	ds_swizzle_b32 v51, v50 offset:swizzle(SWAP,1)
	s_waitcnt lgkmcnt(0)
; __device__ __forceinline__ unsigned pk2(float lo, float hi) { f32x2 v = {lo, hi}; bf16x2_hw b = __builtin_convertvector(v, bf16x2_hw); return __builtin_bit_cast(unsigned, b); }
; __device__ __forceinline__ void diffmix_block(const Grp& G, int b, int h, int qb, float lam, const float* subln, int tid) {
;     ...
;         for (int r = 0; r < 16; ++r) {
;             const float v0 = bflo(a[r]) - lam * bflo(c[r]), v1 = bfhi(a[r]) - lam * bfhi(c[r]);
;             const float ss = wave_sum(v0 * v0 + v1 * v1);
;             const float rs = 1.0f / sqrtf(ss * (1.f / 128.f) + EPSN);
;             *((unsigned*)(G.DO + (row0 + rb + r) * 1024 + h * 128) + lane) = pk2(v0 * rs * g0, v1 * rs * g1);
;         }
	v_add_f32_e32 v50, v50, v51
	ds_swizzle_b32 v51, v50 offset:swizzle(SWAP,2)
	s_waitcnt lgkmcnt(0)
	v_add_f32_e32 v50, v50, v51
	ds_swizzle_b32 v51, v50 offset:swizzle(SWAP,4)
	s_waitcnt lgkmcnt(0)
	v_add_f32_e32 v50, v50, v51
	ds_swizzle_b32 v51, v50 offset:swizzle(SWAP,8)
	s_waitcnt lgkmcnt(0)
	v_add_f32_e32 v50, v50, v51
	ds_swizzle_b32 v51, v50 offset:swizzle(SWAP,16)
	s_waitcnt lgkmcnt(0)
	v_add_f32_e32 v50, v50, v51
	v_mov_b32_e32 v51, v50
	s_nop 1
	v_permlane32_swap_b32_e32 v50, v51
	v_add_f32_e32 v50, v50, v51
	v_fmamk_f32 v50, v50, 0x3c000000, v205
	v_cmp_gt_f32_e32 vcc, s63, v50
	v_mul_f32_e32 v51, 0x4f800000, v50
	s_nop 0
	v_cndmask_b32_e32 v50, v50, v51, vcc
	v_sqrt_f32_e32 v51, v50
	s_nop 0
	v_add_u32_e32 v56, -1, v51
	v_fma_f32 v57, -v56, v51, v50
	v_cmp_ge_f32_e64 s[0:1], 0, v57
	v_add_u32_e32 v57, 1, v51
	s_nop 0
	v_cndmask_b32_e64 v56, v51, v56, s[0:1]
	v_fma_f32 v51, -v57, v51, v50
	v_cmp_lt_f32_e64 s[0:1], 0, v51
	s_nop 1
	v_cndmask_b32_e64 v51, v56, v57, s[0:1]
	v_mul_f32_e32 v56, 0x37800000, v51
	v_cndmask_b32_e32 v51, v51, v56, vcc
	v_cmp_class_f32_e32 vcc, v50, v206
	s_nop 1
	v_cndmask_b32_e32 v50, v51, v50, vcc
	v_rcp_f32_e32 v50, v50
	s_nop 0
	v_pk_mul_f32 v[48:49], v[48:49], v[50:51] op_sel_hi:[1,0]
	s_waitcnt vmcnt(27)
	v_lshlrev_b32_e32 v50, 16, v62
	v_pk_mul_f32 v[48:49], v[0:1], v[48:49]
	v_and_b32_e32 v51, 0xffff0000, v62
	v_cvt_pk_bf16_f32 v48, v48, v49
	global_store_dword v[52:53], v48, off
	v_lshlrev_b32_e32 v48, 16, v61
	v_and_b32_e32 v49, 0xffff0000, v61
	v_pk_fma_f32 v[48:49], v[192:193], v[50:51], v[48:49] neg_lo:[1,0,0] neg_hi:[1,0,0]
	s_nop 0
	v_pk_mul_f32 v[50:51], v[48:49], v[48:49]
	s_nop 0
	v_add_f32_e32 v50, v50, v51
	ds_swizzle_b32 v51, v50 offset:swizzle(SWAP,1)
	s_waitcnt lgkmcnt(0)
	v_add_f32_e32 v50, v50, v51
	ds_swizzle_b32 v51, v50 offset:swizzle(SWAP,2)
	s_waitcnt lgkmcnt(0)
	v_add_f32_e32 v50, v50, v51
	ds_swizzle_b32 v51, v50 offset:swizzle(SWAP,4)
	s_waitcnt lgkmcnt(0)
	v_add_f32_e32 v50, v50, v51
	ds_swizzle_b32 v51, v50 offset:swizzle(SWAP,8)
	s_waitcnt lgkmcnt(0)
	v_add_f32_e32 v50, v50, v51
	ds_swizzle_b32 v51, v50 offset:swizzle(SWAP,16)
	s_waitcnt lgkmcnt(0)
	v_add_f32_e32 v50, v50, v51
	v_mov_b32_e32 v51, v50
	s_nop 1
	v_permlane32_swap_b32_e32 v50, v51
	v_add_f32_e32 v50, v50, v51
	v_fmamk_f32 v50, v50, 0x3c000000, v205
	v_cmp_gt_f32_e32 vcc, s63, v50
	v_mul_f32_e32 v51, 0x4f800000, v50
	s_nop 0
	v_cndmask_b32_e32 v50, v50, v51, vcc
	v_sqrt_f32_e32 v51, v50
	s_nop 0
	v_add_u32_e32 v52, -1, v51
	v_fma_f32 v53, -v52, v51, v50
	v_cmp_ge_f32_e64 s[0:1], 0, v53
	v_add_u32_e32 v53, 1, v51
	s_nop 0
	v_cndmask_b32_e64 v52, v51, v52, s[0:1]
	v_fma_f32 v51, -v53, v51, v50
	v_cmp_lt_f32_e64 s[0:1], 0, v51
	s_nop 1
	v_cndmask_b32_e64 v51, v52, v53, s[0:1]
	v_mul_f32_e32 v52, 0x37800000, v51
	v_cndmask_b32_e32 v51, v51, v52, vcc
	v_cmp_class_f32_e32 vcc, v50, v206
	s_nop 1
	v_cndmask_b32_e32 v50, v51, v50, vcc
	v_rcp_f32_e32 v50, v50
	s_nop 0
	v_pk_mul_f32 v[48:49], v[48:49], v[50:51] op_sel_hi:[1,0]
	s_waitcnt vmcnt(26)
	v_lshlrev_b32_e32 v50, 16, v64
	v_pk_mul_f32 v[48:49], v[0:1], v[48:49]
	v_and_b32_e32 v51, 0xffff0000, v64
	v_cvt_pk_bf16_f32 v48, v48, v49
	global_store_dword v[54:55], v48, off
	v_lshlrev_b32_e32 v48, 16, v63
	v_and_b32_e32 v49, 0xffff0000, v63
	v_pk_fma_f32 v[48:49], v[192:193], v[50:51], v[48:49] neg_lo:[1,0,0] neg_hi:[1,0,0]
	s_nop 0
	v_pk_mul_f32 v[50:51], v[48:49], v[48:49]
	s_nop 0
	v_add_f32_e32 v50, v50, v51
	ds_swizzle_b32 v51, v50 offset:swizzle(SWAP,1)
	s_waitcnt lgkmcnt(0)
	v_add_f32_e32 v50, v50, v51
	ds_swizzle_b32 v51, v50 offset:swizzle(SWAP,2)
	s_waitcnt lgkmcnt(0)
	v_add_f32_e32 v50, v50, v51
	ds_swizzle_b32 v51, v50 offset:swizzle(SWAP,4)
	s_waitcnt lgkmcnt(0)
	v_add_f32_e32 v50, v50, v51
	ds_swizzle_b32 v51, v50 offset:swizzle(SWAP,8)
	s_waitcnt lgkmcnt(0)
	v_add_f32_e32 v50, v50, v51
	ds_swizzle_b32 v51, v50 offset:swizzle(SWAP,16)
	s_waitcnt lgkmcnt(0)
	v_add_f32_e32 v50, v50, v51
	v_mov_b32_e32 v51, v50
	s_nop 1
	v_permlane32_swap_b32_e32 v50, v51
	v_add_f32_e32 v50, v50, v51
	v_fmamk_f32 v50, v50, 0x3c000000, v205
	v_cmp_gt_f32_e32 vcc, s63, v50
	v_mul_f32_e32 v51, 0x4f800000, v50
	s_nop 0
	v_cndmask_b32_e32 v50, v50, v51, vcc
	v_sqrt_f32_e32 v51, v50
	s_nop 0
	v_add_u32_e32 v52, -1, v51
	v_fma_f32 v53, -v52, v51, v50
	v_cmp_ge_f32_e64 s[0:1], 0, v53
	v_add_u32_e32 v53, 1, v51
	s_nop 0
	v_cndmask_b32_e64 v52, v51, v52, s[0:1]
	v_fma_f32 v51, -v53, v51, v50
	v_cmp_lt_f32_e64 s[0:1], 0, v51
	s_nop 1
	v_cndmask_b32_e64 v51, v52, v53, s[0:1]
	v_mul_f32_e32 v52, 0x37800000, v51
	v_cndmask_b32_e32 v51, v51, v52, vcc
	v_cmp_class_f32_e32 vcc, v50, v206
	s_nop 1
	v_cndmask_b32_e32 v50, v51, v50, vcc
	v_rcp_f32_e32 v50, v50
	s_nop 0
	v_pk_mul_f32 v[48:49], v[48:49], v[50:51] op_sel_hi:[1,0]
	s_nop 0
	v_pk_mul_f32 v[48:49], v[0:1], v[48:49]
	s_nop 0
	v_cvt_pk_bf16_f32 v48, v48, v49
	global_store_dword v[32:33], v48, off
	s_waitcnt vmcnt(27)
	v_lshlrev_b32_e32 v32, 16, v65
	s_waitcnt vmcnt(26)
	v_lshlrev_b32_e32 v48, 16, v66
	v_and_b32_e32 v33, 0xffff0000, v65
	v_and_b32_e32 v49, 0xffff0000, v66
	v_pk_fma_f32 v[32:33], v[192:193], v[48:49], v[32:33] neg_lo:[1,0,0] neg_hi:[1,0,0]
	s_nop 0
	v_pk_mul_f32 v[48:49], v[32:33], v[32:33]
	s_nop 0
	v_add_f32_e32 v48, v48, v49
	ds_swizzle_b32 v49, v48 offset:swizzle(SWAP,1)
	s_waitcnt lgkmcnt(0)
	v_add_f32_e32 v48, v48, v49
	ds_swizzle_b32 v49, v48 offset:swizzle(SWAP,2)
	s_waitcnt lgkmcnt(0)
	v_add_f32_e32 v48, v48, v49
	ds_swizzle_b32 v49, v48 offset:swizzle(SWAP,4)
	s_waitcnt lgkmcnt(0)
	v_add_f32_e32 v48, v48, v49
	ds_swizzle_b32 v49, v48 offset:swizzle(SWAP,8)
	s_waitcnt lgkmcnt(0)
; __device__ __forceinline__ unsigned pk2(float lo, float hi) { f32x2 v = {lo, hi}; bf16x2_hw b = __builtin_convertvector(v, bf16x2_hw); return __builtin_bit_cast(unsigned, b); }
; __device__ __forceinline__ void diffmix_block(const Grp& G, int b, int h, int qb, float lam, const float* subln, int tid) {
;     ...
;         for (int r = 0; r < 16; ++r) {
;             const float v0 = bflo(a[r]) - lam * bflo(c[r]), v1 = bfhi(a[r]) - lam * bfhi(c[r]);
;             const float ss = wave_sum(v0 * v0 + v1 * v1);
;             const float rs = 1.0f / sqrtf(ss * (1.f / 128.f) + EPSN);
;             *((unsigned*)(G.DO + (row0 + rb + r) * 1024 + h * 128) + lane) = pk2(v0 * rs * g0, v1 * rs * g1);
;         }
	v_add_f32_e32 v48, v48, v49
	ds_swizzle_b32 v49, v48 offset:swizzle(SWAP,16)
	s_waitcnt lgkmcnt(0)
	v_add_f32_e32 v48, v48, v49
	v_mov_b32_e32 v49, v48
	s_nop 1
	v_permlane32_swap_b32_e32 v48, v49
	v_add_f32_e32 v48, v48, v49
	v_fmamk_f32 v48, v48, 0x3c000000, v205
	v_cmp_gt_f32_e32 vcc, s63, v48
	v_mul_f32_e32 v49, 0x4f800000, v48
	s_nop 0
	v_cndmask_b32_e32 v48, v48, v49, vcc
	v_sqrt_f32_e32 v49, v48
	s_nop 0
	v_add_u32_e32 v50, -1, v49
	v_fma_f32 v51, -v50, v49, v48
	v_cmp_ge_f32_e64 s[0:1], 0, v51
	v_add_u32_e32 v51, 1, v49
	s_nop 0
	v_cndmask_b32_e64 v50, v49, v50, s[0:1]
	v_fma_f32 v49, -v51, v49, v48
	v_cmp_lt_f32_e64 s[0:1], 0, v49
	s_nop 1
	v_cndmask_b32_e64 v49, v50, v51, s[0:1]
	v_mul_f32_e32 v50, 0x37800000, v49
	v_cndmask_b32_e32 v49, v49, v50, vcc
	v_cmp_class_f32_e32 vcc, v48, v206
	s_nop 1
	v_cndmask_b32_e32 v48, v49, v48, vcc
	v_rcp_f32_e32 v48, v48
	s_nop 0
	v_pk_mul_f32 v[32:33], v[32:33], v[48:49] op_sel_hi:[1,0]
	s_nop 0
	v_pk_mul_f32 v[32:33], v[0:1], v[32:33]
	s_nop 0
	v_cvt_pk_bf16_f32 v32, v32, v33
	global_store_dword v[30:31], v32, off
	s_waitcnt vmcnt(26)
	v_lshlrev_b32_e32 v30, 16, v67
	s_waitcnt vmcnt(25)
	v_lshlrev_b32_e32 v32, 16, v68
	v_and_b32_e32 v31, 0xffff0000, v67
	v_and_b32_e32 v33, 0xffff0000, v68
	v_pk_fma_f32 v[30:31], v[192:193], v[32:33], v[30:31] neg_lo:[1,0,0] neg_hi:[1,0,0]
	s_nop 0
	v_pk_mul_f32 v[32:33], v[30:31], v[30:31]
	s_nop 0
	v_add_f32_e32 v32, v32, v33
	ds_swizzle_b32 v33, v32 offset:swizzle(SWAP,1)
	s_waitcnt lgkmcnt(0)
	v_add_f32_e32 v32, v32, v33
	ds_swizzle_b32 v33, v32 offset:swizzle(SWAP,2)
	s_waitcnt lgkmcnt(0)
	v_add_f32_e32 v32, v32, v33
	ds_swizzle_b32 v33, v32 offset:swizzle(SWAP,4)
	s_waitcnt lgkmcnt(0)
	v_add_f32_e32 v32, v32, v33
	ds_swizzle_b32 v33, v32 offset:swizzle(SWAP,8)
	s_waitcnt lgkmcnt(0)
	v_add_f32_e32 v32, v32, v33
	ds_swizzle_b32 v33, v32 offset:swizzle(SWAP,16)
	s_waitcnt lgkmcnt(0)
	v_add_f32_e32 v32, v32, v33
	v_mov_b32_e32 v33, v32
	s_nop 1
	v_permlane32_swap_b32_e32 v32, v33
	v_add_f32_e32 v32, v32, v33
	v_fmamk_f32 v32, v32, 0x3c000000, v205
	v_cmp_gt_f32_e32 vcc, s63, v32
	v_mul_f32_e32 v33, 0x4f800000, v32
	s_nop 0
	v_cndmask_b32_e32 v32, v32, v33, vcc
	v_sqrt_f32_e32 v33, v32
	s_nop 0
	v_add_u32_e32 v48, -1, v33
	v_fma_f32 v49, -v48, v33, v32
	v_cmp_ge_f32_e64 s[0:1], 0, v49
	v_add_u32_e32 v49, 1, v33
	s_nop 0
	v_cndmask_b32_e64 v48, v33, v48, s[0:1]
	v_fma_f32 v33, -v49, v33, v32
	v_cmp_lt_f32_e64 s[0:1], 0, v33
	s_nop 1
	v_cndmask_b32_e64 v33, v48, v49, s[0:1]
	v_mul_f32_e32 v48, 0x37800000, v33
	v_cndmask_b32_e32 v33, v33, v48, vcc
	v_cmp_class_f32_e32 vcc, v32, v206
	s_nop 1
	v_cndmask_b32_e32 v32, v33, v32, vcc
	v_rcp_f32_e32 v32, v32
	s_nop 0
	v_pk_mul_f32 v[30:31], v[30:31], v[32:33] op_sel_hi:[1,0]
	s_nop 0
	v_pk_mul_f32 v[30:31], v[0:1], v[30:31]
	s_nop 0
	v_cvt_pk_bf16_f32 v30, v30, v31
	global_store_dword v[28:29], v30, off
	s_waitcnt vmcnt(25)
	v_lshlrev_b32_e32 v28, 16, v69
	s_waitcnt vmcnt(24)
	v_lshlrev_b32_e32 v30, 16, v70
	v_and_b32_e32 v29, 0xffff0000, v69
	v_and_b32_e32 v31, 0xffff0000, v70
	v_pk_fma_f32 v[28:29], v[192:193], v[30:31], v[28:29] neg_lo:[1,0,0] neg_hi:[1,0,0]
	s_nop 0
	v_pk_mul_f32 v[30:31], v[28:29], v[28:29]
	s_nop 0
	v_add_f32_e32 v30, v30, v31
	ds_swizzle_b32 v31, v30 offset:swizzle(SWAP,1)
	s_waitcnt lgkmcnt(0)
	v_add_f32_e32 v30, v30, v31
	ds_swizzle_b32 v31, v30 offset:swizzle(SWAP,2)
	s_waitcnt lgkmcnt(0)
	v_add_f32_e32 v30, v30, v31
	ds_swizzle_b32 v31, v30 offset:swizzle(SWAP,4)
	s_waitcnt lgkmcnt(0)
	v_add_f32_e32 v30, v30, v31
	ds_swizzle_b32 v31, v30 offset:swizzle(SWAP,8)
	s_waitcnt lgkmcnt(0)
	v_add_f32_e32 v30, v30, v31
	ds_swizzle_b32 v31, v30 offset:swizzle(SWAP,16)
	s_waitcnt lgkmcnt(0)
	v_add_f32_e32 v30, v30, v31
	v_mov_b32_e32 v31, v30
	s_nop 1
	v_permlane32_swap_b32_e32 v30, v31
	v_add_f32_e32 v30, v30, v31
	v_fmamk_f32 v30, v30, 0x3c000000, v205
	v_cmp_gt_f32_e32 vcc, s63, v30
	v_mul_f32_e32 v31, 0x4f800000, v30
	s_nop 0
	v_cndmask_b32_e32 v30, v30, v31, vcc
	v_sqrt_f32_e32 v31, v30
	s_nop 0
	v_add_u32_e32 v32, -1, v31
	v_fma_f32 v33, -v32, v31, v30
	v_cmp_ge_f32_e64 s[0:1], 0, v33
	v_add_u32_e32 v33, 1, v31
	s_nop 0
	v_cndmask_b32_e64 v32, v31, v32, s[0:1]
	v_fma_f32 v31, -v33, v31, v30
	v_cmp_lt_f32_e64 s[0:1], 0, v31
	s_nop 1
	v_cndmask_b32_e64 v31, v32, v33, s[0:1]
	v_mul_f32_e32 v32, 0x37800000, v31
	v_cndmask_b32_e32 v31, v31, v32, vcc
	v_cmp_class_f32_e32 vcc, v30, v206
	s_nop 1
	v_cndmask_b32_e32 v30, v31, v30, vcc
	v_rcp_f32_e32 v30, v30
	s_nop 0
	v_pk_mul_f32 v[28:29], v[28:29], v[30:31] op_sel_hi:[1,0]
	s_nop 0
	v_pk_mul_f32 v[28:29], v[0:1], v[28:29]
	s_nop 0
	v_cvt_pk_bf16_f32 v28, v28, v29
	global_store_dword v[26:27], v28, off
	s_waitcnt vmcnt(24)
	v_lshlrev_b32_e32 v26, 16, v71
	s_waitcnt vmcnt(23)
	v_lshlrev_b32_e32 v28, 16, v72
	v_and_b32_e32 v27, 0xffff0000, v71
	v_and_b32_e32 v29, 0xffff0000, v72
	v_pk_fma_f32 v[26:27], v[192:193], v[28:29], v[26:27] neg_lo:[1,0,0] neg_hi:[1,0,0]
	s_nop 0
	v_pk_mul_f32 v[28:29], v[26:27], v[26:27]
	s_nop 0
	v_add_f32_e32 v28, v28, v29
	ds_swizzle_b32 v29, v28 offset:swizzle(SWAP,1)
	s_waitcnt lgkmcnt(0)
	v_add_f32_e32 v28, v28, v29
	ds_swizzle_b32 v29, v28 offset:swizzle(SWAP,2)
	s_waitcnt lgkmcnt(0)
	v_add_f32_e32 v28, v28, v29
	ds_swizzle_b32 v29, v28 offset:swizzle(SWAP,4)
	s_waitcnt lgkmcnt(0)
	v_add_f32_e32 v28, v28, v29
	ds_swizzle_b32 v29, v28 offset:swizzle(SWAP,8)
	s_waitcnt lgkmcnt(0)
	v_add_f32_e32 v28, v28, v29
	ds_swizzle_b32 v29, v28 offset:swizzle(SWAP,16)
	s_waitcnt lgkmcnt(0)
; __device__ __forceinline__ unsigned pk2(float lo, float hi) { f32x2 v = {lo, hi}; bf16x2_hw b = __builtin_convertvector(v, bf16x2_hw); return __builtin_bit_cast(unsigned, b); }
; __device__ __forceinline__ void diffmix_block(const Grp& G, int b, int h, int qb, float lam, const float* subln, int tid) {
;     ...
;         for (int r = 0; r < 16; ++r) {
;             const float v0 = bflo(a[r]) - lam * bflo(c[r]), v1 = bfhi(a[r]) - lam * bfhi(c[r]);
;             const float ss = wave_sum(v0 * v0 + v1 * v1);
;             const float rs = 1.0f / sqrtf(ss * (1.f / 128.f) + EPSN);
;             *((unsigned*)(G.DO + (row0 + rb + r) * 1024 + h * 128) + lane) = pk2(v0 * rs * g0, v1 * rs * g1);
;         }
	v_add_f32_e32 v28, v28, v29
	v_mov_b32_e32 v29, v28
	s_nop 1
	v_permlane32_swap_b32_e32 v28, v29
	v_add_f32_e32 v28, v28, v29
	v_fmamk_f32 v28, v28, 0x3c000000, v205
	v_cmp_gt_f32_e32 vcc, s63, v28
	v_mul_f32_e32 v29, 0x4f800000, v28
	s_nop 0
	v_cndmask_b32_e32 v28, v28, v29, vcc
	v_sqrt_f32_e32 v29, v28
	s_nop 0
	v_add_u32_e32 v30, -1, v29
	v_fma_f32 v31, -v30, v29, v28
	v_cmp_ge_f32_e64 s[0:1], 0, v31
	v_add_u32_e32 v31, 1, v29
	s_nop 0
	v_cndmask_b32_e64 v30, v29, v30, s[0:1]
	v_fma_f32 v29, -v31, v29, v28
	v_cmp_lt_f32_e64 s[0:1], 0, v29
	s_nop 1
	v_cndmask_b32_e64 v29, v30, v31, s[0:1]
	v_mul_f32_e32 v30, 0x37800000, v29
	v_cndmask_b32_e32 v29, v29, v30, vcc
	v_cmp_class_f32_e32 vcc, v28, v206
	s_nop 1
	v_cndmask_b32_e32 v28, v29, v28, vcc
	v_rcp_f32_e32 v28, v28
	s_nop 0
	v_pk_mul_f32 v[26:27], v[26:27], v[28:29] op_sel_hi:[1,0]
	s_nop 0
	v_pk_mul_f32 v[26:27], v[0:1], v[26:27]
	s_nop 0
	v_cvt_pk_bf16_f32 v26, v26, v27
	global_store_dword v[24:25], v26, off
	s_waitcnt vmcnt(23)
	v_lshlrev_b32_e32 v24, 16, v73
	s_waitcnt vmcnt(22)
	v_lshlrev_b32_e32 v26, 16, v74
	v_and_b32_e32 v25, 0xffff0000, v73
	v_and_b32_e32 v27, 0xffff0000, v74
	v_pk_fma_f32 v[24:25], v[192:193], v[26:27], v[24:25] neg_lo:[1,0,0] neg_hi:[1,0,0]
	s_nop 0
	v_pk_mul_f32 v[26:27], v[24:25], v[24:25]
	s_nop 0
	v_add_f32_e32 v26, v26, v27
	ds_swizzle_b32 v27, v26 offset:swizzle(SWAP,1)
	s_waitcnt lgkmcnt(0)
	v_add_f32_e32 v26, v26, v27
	ds_swizzle_b32 v27, v26 offset:swizzle(SWAP,2)
	s_waitcnt lgkmcnt(0)
	v_add_f32_e32 v26, v26, v27
	ds_swizzle_b32 v27, v26 offset:swizzle(SWAP,4)
	s_waitcnt lgkmcnt(0)
	v_add_f32_e32 v26, v26, v27
	ds_swizzle_b32 v27, v26 offset:swizzle(SWAP,8)
	s_waitcnt lgkmcnt(0)
	v_add_f32_e32 v26, v26, v27
	ds_swizzle_b32 v27, v26 offset:swizzle(SWAP,16)
	s_waitcnt lgkmcnt(0)
	v_add_f32_e32 v26, v26, v27
	v_mov_b32_e32 v27, v26
	s_nop 1
	v_permlane32_swap_b32_e32 v26, v27
	v_add_f32_e32 v26, v26, v27
	v_fmamk_f32 v26, v26, 0x3c000000, v205
	v_cmp_gt_f32_e32 vcc, s63, v26
	v_mul_f32_e32 v27, 0x4f800000, v26
	s_nop 0
	v_cndmask_b32_e32 v26, v26, v27, vcc
	v_sqrt_f32_e32 v27, v26
	s_nop 0
	v_add_u32_e32 v28, -1, v27
	v_fma_f32 v29, -v28, v27, v26
	v_cmp_ge_f32_e64 s[0:1], 0, v29
	v_add_u32_e32 v29, 1, v27
	s_nop 0
	v_cndmask_b32_e64 v28, v27, v28, s[0:1]
	v_fma_f32 v27, -v29, v27, v26
	v_cmp_lt_f32_e64 s[0:1], 0, v27
	s_nop 1
	v_cndmask_b32_e64 v27, v28, v29, s[0:1]
	v_mul_f32_e32 v28, 0x37800000, v27
	v_cndmask_b32_e32 v27, v27, v28, vcc
	v_cmp_class_f32_e32 vcc, v26, v206
	s_nop 1
	v_cndmask_b32_e32 v26, v27, v26, vcc
	v_rcp_f32_e32 v26, v26
	s_nop 0
	v_pk_mul_f32 v[24:25], v[24:25], v[26:27] op_sel_hi:[1,0]
	s_nop 0
	v_pk_mul_f32 v[24:25], v[0:1], v[24:25]
	s_nop 0
	v_cvt_pk_bf16_f32 v24, v24, v25
	global_store_dword v[22:23], v24, off
	s_waitcnt vmcnt(22)
	v_lshlrev_b32_e32 v22, 16, v46
	s_waitcnt vmcnt(21)
	v_lshlrev_b32_e32 v24, 16, v47
	v_and_b32_e32 v23, 0xffff0000, v46
	v_and_b32_e32 v25, 0xffff0000, v47
	v_pk_fma_f32 v[22:23], v[192:193], v[24:25], v[22:23] neg_lo:[1,0,0] neg_hi:[1,0,0]
	s_nop 0
	v_pk_mul_f32 v[24:25], v[22:23], v[22:23]
	s_nop 0
	v_add_f32_e32 v24, v24, v25
	ds_swizzle_b32 v25, v24 offset:swizzle(SWAP,1)
	s_waitcnt lgkmcnt(0)
	v_add_f32_e32 v24, v24, v25
	ds_swizzle_b32 v25, v24 offset:swizzle(SWAP,2)
	s_waitcnt lgkmcnt(0)
	v_add_f32_e32 v24, v24, v25
	ds_swizzle_b32 v25, v24 offset:swizzle(SWAP,4)
	s_waitcnt lgkmcnt(0)
	v_add_f32_e32 v24, v24, v25
	ds_swizzle_b32 v25, v24 offset:swizzle(SWAP,8)
	s_waitcnt lgkmcnt(0)
	v_add_f32_e32 v24, v24, v25
	ds_swizzle_b32 v25, v24 offset:swizzle(SWAP,16)
	s_waitcnt lgkmcnt(0)
	v_add_f32_e32 v24, v24, v25
	v_mov_b32_e32 v25, v24
	s_nop 1
	v_permlane32_swap_b32_e32 v24, v25
	v_add_f32_e32 v24, v24, v25
	v_fmamk_f32 v24, v24, 0x3c000000, v205
	v_cmp_gt_f32_e32 vcc, s63, v24
	v_mul_f32_e32 v25, 0x4f800000, v24
	s_nop 0
	v_cndmask_b32_e32 v24, v24, v25, vcc
	v_sqrt_f32_e32 v25, v24
	s_nop 0
	v_add_u32_e32 v26, -1, v25
	v_fma_f32 v27, -v26, v25, v24
	v_cmp_ge_f32_e64 s[0:1], 0, v27
	v_add_u32_e32 v27, 1, v25
	s_nop 0
	v_cndmask_b32_e64 v26, v25, v26, s[0:1]
	v_fma_f32 v25, -v27, v25, v24
	v_cmp_lt_f32_e64 s[0:1], 0, v25
	s_nop 1
	v_cndmask_b32_e64 v25, v26, v27, s[0:1]
	v_mul_f32_e32 v26, 0x37800000, v25
	v_cndmask_b32_e32 v25, v25, v26, vcc
	v_cmp_class_f32_e32 vcc, v24, v206
	s_nop 1
	v_cndmask_b32_e32 v24, v25, v24, vcc
	v_rcp_f32_e32 v24, v24
	s_nop 0
	v_pk_mul_f32 v[22:23], v[22:23], v[24:25] op_sel_hi:[1,0]
	s_nop 0
	v_pk_mul_f32 v[22:23], v[0:1], v[22:23]
	s_nop 0
	v_cvt_pk_bf16_f32 v22, v22, v23
	global_store_dword v[20:21], v22, off
	s_waitcnt vmcnt(21)
	v_lshlrev_b32_e32 v20, 16, v44
	s_waitcnt vmcnt(20)
	v_lshlrev_b32_e32 v22, 16, v45
	v_and_b32_e32 v21, 0xffff0000, v44
	v_and_b32_e32 v23, 0xffff0000, v45
	v_pk_fma_f32 v[20:21], v[192:193], v[22:23], v[20:21] neg_lo:[1,0,0] neg_hi:[1,0,0]
	s_nop 0
	v_pk_mul_f32 v[22:23], v[20:21], v[20:21]
	s_nop 0
	v_add_f32_e32 v22, v22, v23
	ds_swizzle_b32 v23, v22 offset:swizzle(SWAP,1)
	s_waitcnt lgkmcnt(0)
	v_add_f32_e32 v22, v22, v23
	ds_swizzle_b32 v23, v22 offset:swizzle(SWAP,2)
	s_waitcnt lgkmcnt(0)
	v_add_f32_e32 v22, v22, v23
	ds_swizzle_b32 v23, v22 offset:swizzle(SWAP,4)
	s_waitcnt lgkmcnt(0)
	v_add_f32_e32 v22, v22, v23
	ds_swizzle_b32 v23, v22 offset:swizzle(SWAP,8)
	s_waitcnt lgkmcnt(0)
	v_add_f32_e32 v22, v22, v23
	ds_swizzle_b32 v23, v22 offset:swizzle(SWAP,16)
	s_waitcnt lgkmcnt(0)
; __device__ __forceinline__ unsigned pk2(float lo, float hi) { f32x2 v = {lo, hi}; bf16x2_hw b = __builtin_convertvector(v, bf16x2_hw); return __builtin_bit_cast(unsigned, b); }
; __device__ __forceinline__ void diffmix_block(const Grp& G, int b, int h, int qb, float lam, const float* subln, int tid) {
;     ...
;         for (int r = 0; r < 16; ++r) {
;             const float v0 = bflo(a[r]) - lam * bflo(c[r]), v1 = bfhi(a[r]) - lam * bfhi(c[r]);
;             const float ss = wave_sum(v0 * v0 + v1 * v1);
;             const float rs = 1.0f / sqrtf(ss * (1.f / 128.f) + EPSN);
;             *((unsigned*)(G.DO + (row0 + rb + r) * 1024 + h * 128) + lane) = pk2(v0 * rs * g0, v1 * rs * g1);
;         }
	v_add_f32_e32 v22, v22, v23
	v_mov_b32_e32 v23, v22
	s_nop 1
	v_permlane32_swap_b32_e32 v22, v23
	v_add_f32_e32 v22, v22, v23
	v_fmamk_f32 v22, v22, 0x3c000000, v205
	v_cmp_gt_f32_e32 vcc, s63, v22
	v_mul_f32_e32 v23, 0x4f800000, v22
	s_nop 0
	v_cndmask_b32_e32 v22, v22, v23, vcc
	v_sqrt_f32_e32 v23, v22
	s_nop 0
	v_add_u32_e32 v24, -1, v23
	v_fma_f32 v25, -v24, v23, v22
	v_cmp_ge_f32_e64 s[0:1], 0, v25
	v_add_u32_e32 v25, 1, v23
	s_nop 0
	v_cndmask_b32_e64 v24, v23, v24, s[0:1]
	v_fma_f32 v23, -v25, v23, v22
	v_cmp_lt_f32_e64 s[0:1], 0, v23
	s_nop 1
	v_cndmask_b32_e64 v23, v24, v25, s[0:1]
	v_mul_f32_e32 v24, 0x37800000, v23
	v_cndmask_b32_e32 v23, v23, v24, vcc
	v_cmp_class_f32_e32 vcc, v22, v206
	s_nop 1
	v_cndmask_b32_e32 v22, v23, v22, vcc
	v_rcp_f32_e32 v22, v22
	s_nop 0
	v_pk_mul_f32 v[20:21], v[20:21], v[22:23] op_sel_hi:[1,0]
	s_nop 0
	v_pk_mul_f32 v[20:21], v[0:1], v[20:21]
	s_nop 0
	v_cvt_pk_bf16_f32 v20, v20, v21
	global_store_dword v[18:19], v20, off
	s_waitcnt vmcnt(20)
	v_lshlrev_b32_e32 v18, 16, v42
	s_waitcnt vmcnt(19)
	v_lshlrev_b32_e32 v20, 16, v43
	v_and_b32_e32 v19, 0xffff0000, v42
	v_and_b32_e32 v21, 0xffff0000, v43
	v_pk_fma_f32 v[18:19], v[192:193], v[20:21], v[18:19] neg_lo:[1,0,0] neg_hi:[1,0,0]
	s_nop 0
	v_pk_mul_f32 v[20:21], v[18:19], v[18:19]
	s_nop 0
	v_add_f32_e32 v20, v20, v21
	ds_swizzle_b32 v21, v20 offset:swizzle(SWAP,1)
	s_waitcnt lgkmcnt(0)
	v_add_f32_e32 v20, v20, v21
	ds_swizzle_b32 v21, v20 offset:swizzle(SWAP,2)
	s_waitcnt lgkmcnt(0)
	v_add_f32_e32 v20, v20, v21
	ds_swizzle_b32 v21, v20 offset:swizzle(SWAP,4)
	s_waitcnt lgkmcnt(0)
	v_add_f32_e32 v20, v20, v21
	ds_swizzle_b32 v21, v20 offset:swizzle(SWAP,8)
	s_waitcnt lgkmcnt(0)
	v_add_f32_e32 v20, v20, v21
	ds_swizzle_b32 v21, v20 offset:swizzle(SWAP,16)
	s_waitcnt lgkmcnt(0)
	v_add_f32_e32 v20, v20, v21
	v_mov_b32_e32 v21, v20
	s_nop 1
	v_permlane32_swap_b32_e32 v20, v21
	v_add_f32_e32 v20, v20, v21
	v_fmamk_f32 v20, v20, 0x3c000000, v205
	v_cmp_gt_f32_e32 vcc, s63, v20
	v_mul_f32_e32 v21, 0x4f800000, v20
	s_nop 0
	v_cndmask_b32_e32 v20, v20, v21, vcc
	v_sqrt_f32_e32 v21, v20
	s_nop 0
	v_add_u32_e32 v22, -1, v21
	v_fma_f32 v23, -v22, v21, v20
	v_cmp_ge_f32_e64 s[0:1], 0, v23
	v_add_u32_e32 v23, 1, v21
	s_nop 0
	v_cndmask_b32_e64 v22, v21, v22, s[0:1]
	v_fma_f32 v21, -v23, v21, v20
	v_cmp_lt_f32_e64 s[0:1], 0, v21
	s_nop 1
	v_cndmask_b32_e64 v21, v22, v23, s[0:1]
	v_mul_f32_e32 v22, 0x37800000, v21
	v_cndmask_b32_e32 v21, v21, v22, vcc
	v_cmp_class_f32_e32 vcc, v20, v206
	s_nop 1
	v_cndmask_b32_e32 v20, v21, v20, vcc
	v_rcp_f32_e32 v20, v20
	s_nop 0
	v_pk_mul_f32 v[18:19], v[18:19], v[20:21] op_sel_hi:[1,0]
	s_nop 0
	v_pk_mul_f32 v[18:19], v[0:1], v[18:19]
	s_nop 0
	v_cvt_pk_bf16_f32 v18, v18, v19
	global_store_dword v[16:17], v18, off
	s_waitcnt vmcnt(19)
	v_lshlrev_b32_e32 v16, 16, v40
	s_waitcnt vmcnt(18)
	v_lshlrev_b32_e32 v18, 16, v41
	v_and_b32_e32 v17, 0xffff0000, v40
	v_and_b32_e32 v19, 0xffff0000, v41
	v_pk_fma_f32 v[16:17], v[192:193], v[18:19], v[16:17] neg_lo:[1,0,0] neg_hi:[1,0,0]
	s_nop 0
	v_pk_mul_f32 v[18:19], v[16:17], v[16:17]
	s_nop 0
	v_add_f32_e32 v18, v18, v19
	ds_swizzle_b32 v19, v18 offset:swizzle(SWAP,1)
	s_waitcnt lgkmcnt(0)
	v_add_f32_e32 v18, v18, v19
	ds_swizzle_b32 v19, v18 offset:swizzle(SWAP,2)
	s_waitcnt lgkmcnt(0)
	v_add_f32_e32 v18, v18, v19
	ds_swizzle_b32 v19, v18 offset:swizzle(SWAP,4)
	s_waitcnt lgkmcnt(0)
	v_add_f32_e32 v18, v18, v19
	ds_swizzle_b32 v19, v18 offset:swizzle(SWAP,8)
	s_waitcnt lgkmcnt(0)
	v_add_f32_e32 v18, v18, v19
	ds_swizzle_b32 v19, v18 offset:swizzle(SWAP,16)
	s_waitcnt lgkmcnt(0)
	v_add_f32_e32 v18, v18, v19
	v_mov_b32_e32 v19, v18
	s_nop 1
	v_permlane32_swap_b32_e32 v18, v19
	v_add_f32_e32 v18, v18, v19
	v_fmamk_f32 v18, v18, 0x3c000000, v205
	v_cmp_gt_f32_e32 vcc, s63, v18
	v_mul_f32_e32 v19, 0x4f800000, v18
	s_nop 0
	v_cndmask_b32_e32 v18, v18, v19, vcc
	v_sqrt_f32_e32 v19, v18
	s_nop 0
	v_add_u32_e32 v20, -1, v19
	v_fma_f32 v21, -v20, v19, v18
	v_cmp_ge_f32_e64 s[0:1], 0, v21
	v_add_u32_e32 v21, 1, v19
	s_nop 0
	v_cndmask_b32_e64 v20, v19, v20, s[0:1]
	v_fma_f32 v19, -v21, v19, v18
	v_cmp_lt_f32_e64 s[0:1], 0, v19
	s_nop 1
	v_cndmask_b32_e64 v19, v20, v21, s[0:1]
	v_mul_f32_e32 v20, 0x37800000, v19
	v_cndmask_b32_e32 v19, v19, v20, vcc
	v_cmp_class_f32_e32 vcc, v18, v206
	s_nop 1
	v_cndmask_b32_e32 v18, v19, v18, vcc
	v_rcp_f32_e32 v18, v18
	s_nop 0
	v_pk_mul_f32 v[16:17], v[16:17], v[18:19] op_sel_hi:[1,0]
	s_nop 0
	v_pk_mul_f32 v[16:17], v[0:1], v[16:17]
	s_nop 0
	v_cvt_pk_bf16_f32 v16, v16, v17
	global_store_dword v[14:15], v16, off
	s_waitcnt vmcnt(18)
	v_lshlrev_b32_e32 v14, 16, v38
	s_waitcnt vmcnt(17)
	v_lshlrev_b32_e32 v16, 16, v39
	v_and_b32_e32 v15, 0xffff0000, v38
	v_and_b32_e32 v17, 0xffff0000, v39
	v_pk_fma_f32 v[14:15], v[192:193], v[16:17], v[14:15] neg_lo:[1,0,0] neg_hi:[1,0,0]
	s_nop 0
	v_pk_mul_f32 v[16:17], v[14:15], v[14:15]
	s_nop 0
	v_add_f32_e32 v16, v16, v17
	ds_swizzle_b32 v17, v16 offset:swizzle(SWAP,1)
	s_waitcnt lgkmcnt(0)
	v_add_f32_e32 v16, v16, v17
	ds_swizzle_b32 v17, v16 offset:swizzle(SWAP,2)
	s_waitcnt lgkmcnt(0)
	v_add_f32_e32 v16, v16, v17
	ds_swizzle_b32 v17, v16 offset:swizzle(SWAP,4)
	s_waitcnt lgkmcnt(0)
	v_add_f32_e32 v16, v16, v17
	ds_swizzle_b32 v17, v16 offset:swizzle(SWAP,8)
	s_waitcnt lgkmcnt(0)
	v_add_f32_e32 v16, v16, v17
	ds_swizzle_b32 v17, v16 offset:swizzle(SWAP,16)
	s_waitcnt lgkmcnt(0)
; __device__ __forceinline__ unsigned pk2(float lo, float hi) { f32x2 v = {lo, hi}; bf16x2_hw b = __builtin_convertvector(v, bf16x2_hw); return __builtin_bit_cast(unsigned, b); }
; __device__ __forceinline__ void diffmix_block(const Grp& G, int b, int h, int qb, float lam, const float* subln, int tid) {
;     ...
;         for (int r = 0; r < 16; ++r) {
;             const float v0 = bflo(a[r]) - lam * bflo(c[r]), v1 = bfhi(a[r]) - lam * bfhi(c[r]);
;             const float ss = wave_sum(v0 * v0 + v1 * v1);
;             const float rs = 1.0f / sqrtf(ss * (1.f / 128.f) + EPSN);
;             *((unsigned*)(G.DO + (row0 + rb + r) * 1024 + h * 128) + lane) = pk2(v0 * rs * g0, v1 * rs * g1);
;         }
	v_add_f32_e32 v16, v16, v17
	v_mov_b32_e32 v17, v16
	s_nop 1
	v_permlane32_swap_b32_e32 v16, v17
	v_add_f32_e32 v16, v16, v17
	v_fmamk_f32 v16, v16, 0x3c000000, v205
	v_cmp_gt_f32_e32 vcc, s63, v16
	v_mul_f32_e32 v17, 0x4f800000, v16
	s_nop 0
	v_cndmask_b32_e32 v16, v16, v17, vcc
	v_sqrt_f32_e32 v17, v16
	s_nop 0
	v_add_u32_e32 v18, -1, v17
	v_fma_f32 v19, -v18, v17, v16
	v_cmp_ge_f32_e64 s[0:1], 0, v19
	v_add_u32_e32 v19, 1, v17
	s_nop 0
	v_cndmask_b32_e64 v18, v17, v18, s[0:1]
	v_fma_f32 v17, -v19, v17, v16
	v_cmp_lt_f32_e64 s[0:1], 0, v17
	s_nop 1
	v_cndmask_b32_e64 v17, v18, v19, s[0:1]
	v_mul_f32_e32 v18, 0x37800000, v17
	v_cndmask_b32_e32 v17, v17, v18, vcc
	v_cmp_class_f32_e32 vcc, v16, v206
	s_nop 1
	v_cndmask_b32_e32 v16, v17, v16, vcc
	v_rcp_f32_e32 v16, v16
	s_nop 0
	v_pk_mul_f32 v[14:15], v[14:15], v[16:17] op_sel_hi:[1,0]
	s_nop 0
	v_pk_mul_f32 v[14:15], v[0:1], v[14:15]
	s_nop 0
	v_cvt_pk_bf16_f32 v14, v14, v15
	global_store_dword v[12:13], v14, off
	s_waitcnt vmcnt(17)
	v_lshlrev_b32_e32 v12, 16, v36
	s_waitcnt vmcnt(16)
	v_lshlrev_b32_e32 v14, 16, v37
	v_and_b32_e32 v13, 0xffff0000, v36
	v_and_b32_e32 v15, 0xffff0000, v37
	v_pk_fma_f32 v[12:13], v[192:193], v[14:15], v[12:13] neg_lo:[1,0,0] neg_hi:[1,0,0]
	s_nop 0
	v_pk_mul_f32 v[14:15], v[12:13], v[12:13]
	s_nop 0
	v_add_f32_e32 v14, v14, v15
	ds_swizzle_b32 v15, v14 offset:swizzle(SWAP,1)
	s_waitcnt lgkmcnt(0)
	v_add_f32_e32 v14, v14, v15
	ds_swizzle_b32 v15, v14 offset:swizzle(SWAP,2)
	s_waitcnt lgkmcnt(0)
	v_add_f32_e32 v14, v14, v15
	ds_swizzle_b32 v15, v14 offset:swizzle(SWAP,4)
	s_waitcnt lgkmcnt(0)
	v_add_f32_e32 v14, v14, v15
	ds_swizzle_b32 v15, v14 offset:swizzle(SWAP,8)
	s_waitcnt lgkmcnt(0)
	v_add_f32_e32 v14, v14, v15
	ds_swizzle_b32 v15, v14 offset:swizzle(SWAP,16)
	s_waitcnt lgkmcnt(0)
	v_add_f32_e32 v14, v14, v15
	v_mov_b32_e32 v15, v14
	s_nop 1
	v_permlane32_swap_b32_e32 v14, v15
	v_add_f32_e32 v14, v14, v15
	v_fmamk_f32 v14, v14, 0x3c000000, v205
	v_cmp_gt_f32_e32 vcc, s63, v14
	v_mul_f32_e32 v15, 0x4f800000, v14
	s_nop 0
	v_cndmask_b32_e32 v14, v14, v15, vcc
	v_sqrt_f32_e32 v15, v14
	s_nop 0
	v_add_u32_e32 v16, -1, v15
	v_fma_f32 v17, -v16, v15, v14
	v_cmp_ge_f32_e64 s[0:1], 0, v17
	v_add_u32_e32 v17, 1, v15
	s_nop 0
	v_cndmask_b32_e64 v16, v15, v16, s[0:1]
	v_fma_f32 v15, -v17, v15, v14
	v_cmp_lt_f32_e64 s[0:1], 0, v15
	s_nop 1
	v_cndmask_b32_e64 v15, v16, v17, s[0:1]
	v_mul_f32_e32 v16, 0x37800000, v15
	v_cndmask_b32_e32 v15, v15, v16, vcc
	v_cmp_class_f32_e32 vcc, v14, v206
	s_nop 1
	v_cndmask_b32_e32 v14, v15, v14, vcc
	v_rcp_f32_e32 v14, v14
	s_nop 0
	v_pk_mul_f32 v[12:13], v[12:13], v[14:15] op_sel_hi:[1,0]
	s_nop 0
	v_pk_mul_f32 v[12:13], v[0:1], v[12:13]
	s_nop 0
	v_cvt_pk_bf16_f32 v12, v12, v13
	global_store_dword v[10:11], v12, off
	s_waitcnt vmcnt(16)
	v_lshlrev_b32_e32 v10, 16, v34
	s_waitcnt vmcnt(15)
	v_lshlrev_b32_e32 v12, 16, v35
	v_and_b32_e32 v11, 0xffff0000, v34
	v_and_b32_e32 v13, 0xffff0000, v35
	v_pk_fma_f32 v[10:11], v[192:193], v[12:13], v[10:11] neg_lo:[1,0,0] neg_hi:[1,0,0]
	s_nop 0
	v_pk_mul_f32 v[12:13], v[10:11], v[10:11]
	s_nop 0
	v_add_f32_e32 v12, v12, v13
	ds_swizzle_b32 v13, v12 offset:swizzle(SWAP,1)
	s_waitcnt lgkmcnt(0)
	v_add_f32_e32 v12, v12, v13
	ds_swizzle_b32 v13, v12 offset:swizzle(SWAP,2)
	s_waitcnt lgkmcnt(0)
	v_add_f32_e32 v12, v12, v13
	ds_swizzle_b32 v13, v12 offset:swizzle(SWAP,4)
	s_waitcnt lgkmcnt(0)
	v_add_f32_e32 v12, v12, v13
	ds_swizzle_b32 v13, v12 offset:swizzle(SWAP,8)
	s_waitcnt lgkmcnt(0)
	v_add_f32_e32 v12, v12, v13
	ds_swizzle_b32 v13, v12 offset:swizzle(SWAP,16)
	s_waitcnt lgkmcnt(0)
	v_add_f32_e32 v12, v12, v13
	v_mov_b32_e32 v13, v12
	s_nop 1
	v_permlane32_swap_b32_e32 v12, v13
	v_add_f32_e32 v12, v12, v13
	v_fmamk_f32 v12, v12, 0x3c000000, v205
	v_cmp_gt_f32_e32 vcc, s63, v12
	v_mul_f32_e32 v13, 0x4f800000, v12
	s_nop 0
	v_cndmask_b32_e32 v12, v12, v13, vcc
	v_sqrt_f32_e32 v13, v12
	s_nop 0
	v_add_u32_e32 v14, -1, v13
	v_fma_f32 v15, -v14, v13, v12
	v_cmp_ge_f32_e64 s[0:1], 0, v15
	v_add_u32_e32 v15, 1, v13
	s_nop 0
	v_cndmask_b32_e64 v14, v13, v14, s[0:1]
	v_fma_f32 v13, -v15, v13, v12
	v_cmp_lt_f32_e64 s[0:1], 0, v13
	s_nop 1
	v_cndmask_b32_e64 v13, v14, v15, s[0:1]
	v_mul_f32_e32 v14, 0x37800000, v13
	v_cndmask_b32_e32 v13, v13, v14, vcc
	v_cmp_class_f32_e32 vcc, v12, v206
	s_nop 1
	v_cndmask_b32_e32 v12, v13, v12, vcc
	s_mov_b64 s[0:1], 16
	v_rcp_f32_e32 v12, v12
	s_nop 0
	v_pk_mul_f32 v[10:11], v[10:11], v[12:13] op_sel_hi:[1,0]
	s_and_b64 vcc, exec, s[2:3]
	v_pk_mul_f32 v[10:11], v[0:1], v[10:11]
	s_mov_b64 s[2:3], 0
	v_cvt_pk_bf16_f32 v10, v10, v11
	global_store_dword v[8:9], v10, off
	s_cbranch_vccnz .LBB0_557
	s_mov_b32 s2, 64
	s_mov_b64 s[0:1], 0
	s_and_b64 vcc, exec, s[20:21]
	s_cbranch_vccz .LBB0_515
	s_bfe_u32 s0, s87, 0x40002
	s_lshl_b32 s1, s0, 6
	s_lshl_b32 s0, s0, 7
	v_readlane_b32 s2, v246, 4
	v_readlane_b32 s3, v246, 5
	s_add_u32 s12, s2, s0
	s_addc_u32 s13, s3, 0
	v_readlane_b32 s2, v246, 10
	v_readlane_b32 s3, v246, 11
	s_add_u32 s14, s2, s1
	s_addc_u32 s15, s3, 0
	v_readlane_b32 s1, v246, 8
	s_add_u32 s16, s1, s0
	v_readlane_b32 s1, v246, 9
	s_addc_u32 s17, s1, 0
	v_readlane_b32 s1, v246, 6
	s_add_u32 s18, s1, s0
	v_readlane_b32 s1, v246, 7
	s_addc_u32 s19, s1, 0
	v_readlane_b32 s1, v246, 14
	s_add_u32 s42, s1, s0
	v_readlane_b32 s1, v246, 16
	s_addc_u32 s43, s1, 0
	v_readlane_b32 s1, v246, 18
	s_add_u32 s44, s1, s0
	v_readlane_b32 s0, v246, 19
	s_addc_u32 s45, s0, 0
	v_readlane_b32 s0, v247, 36
	s_mov_b32 s46, 0
	s_mov_b32 s86, s0
	v_readlane_b32 s1, v247, 37
	s_branch .LBB0_561

; __device__ __forceinline__ unsigned f2bf(float f) { return pk2(f, 0.f) & 0xffffu; }
; __device__ __forceinline__ int crow(int r, int hi) { return (r & 3) + 8 * (r >> 2) + 4 * hi; }
; __device__ __forceinline__ float xsum32(float v) { auto rr = __builtin_amdgcn_permlane32_swap(__float_as_uint(v), __float_as_uint(v), false, false); return __uint_as_float(rr[0]) + __uint_as_float(rr[1]); }
; template <bool DIFF>
; __device__ __forceinline__ void attn_unit_coop(const Grp& G, int b, int h, int qb, int n, LAS unsigned char* lds, const int tid_in) {
;     ...
;         const float lt = xsum32(st.l);
;         if (hi == 0) wsf[32 + q] = lt;
;         float inv[16];
; #pragma unroll
;         for (int r = 0; r < 16; ++r) inv[r] = 1.0f / wsf[32 + crow(r, hi)];
;         bf16* obase = (DIFF ? (n == 0 ? G.DO : G.XN) + h * 128 : G.MO + h * 64) + (seq0 + qrow0) * 1024 + q;
; #pragma unroll
;         for (int db = 0; db < NDB; ++db)
; #pragma unroll
;             for (int r = 0; r < 16; ++r) obase[(size_t)crow(r, hi) * 1024 + db * 32] = (bf16)f2bf(st.o[db][r] * inv[r]);
.LBB0_562:
	s_or_b64 exec, exec, s[0:1]
	ds_read_b128 v[36:39], v155 offset:6272
	ds_read_b128 v[32:35], v155 offset:6304
	v_lshlrev_b32_e32 v184, 1, v154
	s_mov_b64 s[2:3], 0
	s_waitcnt lgkmcnt(1)
	v_rcp_f32_e32 v36, v36
	s_nop 0
	v_mul_f32_e32 v16, v16, v36
	v_mul_f32_e32 v0, v0, v36
	v_rcp_f32_e32 v37, v37
	v_rcp_f32_e32 v38, v38
	v_rcp_f32_e32 v39, v39
	s_waitcnt lgkmcnt(0)
	v_rcp_f32_e32 v40, v32
	s_nop 0
	v_mul_f32_e32 v20, v20, v40
	v_rcp_f32_e32 v41, v33
	v_rcp_f32_e32 v42, v34
	s_nop 0
	v_mul_f32_e32 v22, v22, v42
	v_rcp_f32_e32 v43, v35
	ds_read_b128 v[32:35], v155 offset:6336
	s_waitcnt lgkmcnt(0)
	v_rcp_f32_e32 v44, v32
	s_nop 0
	v_mul_f32_e32 v24, v24, v44
	v_rcp_f32_e32 v45, v33
	v_rcp_f32_e32 v46, v34
	s_nop 0
	v_mul_f32_e32 v26, v26, v46
	v_rcp_f32_e32 v47, v35
	ds_read_b128 v[32:35], v155 offset:6368
	s_waitcnt lgkmcnt(0)
	v_rcp_f32_e32 v62, v32
	s_nop 0
	v_mul_f32_e32 v28, v28, v62
	v_rcp_f32_e32 v63, v33
	v_rcp_f32_e32 v64, v34
	s_lshl_b64 s[0:1], s[30:31], 11
	s_add_u32 s0, s12, s0
	s_addc_u32 s1, s13, s1
	v_rcp_f32_e32 v65, v35
	v_lshl_add_u64 v[32:33], s[0:1], 0, v[184:185]
	v_lshlrev_b32_e32 v184, 13, v153
	v_cvt_pk_bf16_f32 v16, v16, s0
	v_lshl_add_u64 v[34:35], v[32:33], 0, v[184:185]
	global_store_short v[34:35], v16, off
	v_mul_f32_e32 v16, v17, v37
	v_cvt_pk_bf16_f32 v16, v16, s0
	global_store_short v[34:35], v16, off offset:2048
	v_mul_f32_e32 v16, v18, v38
	v_cvt_pk_bf16_f32 v18, v16, s0
	v_or_b32_e32 v16, 0x1000, v184
	v_mov_b32_e32 v17, v185
	v_lshl_add_u64 v[48:49], v[32:33], 0, v[16:17]
	global_store_short v[48:49], v18, off
	v_mul_f32_e32 v18, v19, v39
	v_cvt_pk_bf16_f32 v50, v18, s0
	v_or_b32_e32 v18, 0x1800, v184
	v_mov_b32_e32 v19, v185
	v_lshl_add_u64 v[48:49], v[32:33], 0, v[18:19]
	global_store_short v[48:49], v50, off
	v_or_b32_e32 v48, 0x4000, v184
	v_mov_b32_e32 v49, v185
	v_cvt_pk_bf16_f32 v20, v20, s0
	v_lshl_add_u64 v[50:51], v[32:33], 0, v[48:49]
	global_store_short v[50:51], v20, off
	v_mul_f32_e32 v20, v21, v41
	v_cvt_pk_bf16_f32 v52, v20, s0
	v_or_b32_e32 v20, 0x4800, v184
	v_mov_b32_e32 v21, v185
	v_lshl_add_u64 v[50:51], v[32:33], 0, v[20:21]
	global_store_short v[50:51], v52, off
	v_or_b32_e32 v50, 0x5000, v184
	v_mov_b32_e32 v51, v185
	v_cvt_pk_bf16_f32 v22, v22, s0
	v_lshl_add_u64 v[52:53], v[32:33], 0, v[50:51]
	global_store_short v[52:53], v22, off
	v_mul_f32_e32 v22, v23, v43
	v_cvt_pk_bf16_f32 v54, v22, s0
	v_or_b32_e32 v22, 0x5800, v184
	v_mov_b32_e32 v23, v185
	v_lshl_add_u64 v[52:53], v[32:33], 0, v[22:23]
	global_store_short v[52:53], v54, off
	v_or_b32_e32 v52, 0x8000, v184
	v_mov_b32_e32 v53, v185
	v_cvt_pk_bf16_f32 v24, v24, s0
	v_lshl_add_u64 v[54:55], v[32:33], 0, v[52:53]
	global_store_short v[54:55], v24, off
	v_mul_f32_e32 v24, v25, v45
	v_cvt_pk_bf16_f32 v56, v24, s0
	v_or_b32_e32 v24, 0x8800, v184
	v_mov_b32_e32 v25, v185
	v_lshl_add_u64 v[54:55], v[32:33], 0, v[24:25]
	global_store_short v[54:55], v56, off
	v_or_b32_e32 v54, 0x9000, v184
	v_mov_b32_e32 v55, v185
	v_cvt_pk_bf16_f32 v26, v26, s0
	v_lshl_add_u64 v[56:57], v[32:33], 0, v[54:55]
	global_store_short v[56:57], v26, off
	v_mul_f32_e32 v26, v27, v47
	v_cvt_pk_bf16_f32 v58, v26, s0
	v_or_b32_e32 v26, 0x9800, v184
	v_mov_b32_e32 v27, v185
	v_lshl_add_u64 v[56:57], v[32:33], 0, v[26:27]
	global_store_short v[56:57], v58, off
	v_or_b32_e32 v56, 0xc000, v184
	v_mov_b32_e32 v57, v185
	v_cvt_pk_bf16_f32 v28, v28, s0
	v_lshl_add_u64 v[58:59], v[32:33], 0, v[56:57]
	global_store_short v[58:59], v28, off
	v_mul_f32_e32 v28, v29, v63
	v_cvt_pk_bf16_f32 v60, v28, s0
	v_or_b32_e32 v28, 0xc800, v184
	v_mov_b32_e32 v29, v185
	v_lshl_add_u64 v[58:59], v[32:33], 0, v[28:29]
	global_store_short v[58:59], v60, off
	v_mul_f32_e32 v30, v30, v64
	v_or_b32_e32 v58, 0xd000, v184
	v_mov_b32_e32 v59, v185
	v_cvt_pk_bf16_f32 v30, v30, s0
	v_lshl_add_u64 v[60:61], v[32:33], 0, v[58:59]
	v_cvt_pk_bf16_f32 v0, v0, s0
	global_store_short v[60:61], v30, off
	v_mul_f32_e32 v30, v31, v65
	v_or_b32_e32 v184, 0xd800, v184
	global_store_short v[34:35], v0, off offset:64
	v_mul_f32_e32 v0, v1, v37
	v_cvt_pk_bf16_f32 v60, v30, s0
	v_lshl_add_u64 v[30:31], v[32:33], 0, v[184:185]
	v_cvt_pk_bf16_f32 v0, v0, s0
	global_store_short v[30:31], v60, off
	v_lshl_add_u64 v[30:31], v[32:33], 0, 64
	global_store_short v[34:35], v0, off offset:2112
	v_mul_f32_e32 v0, v2, v38
	v_cvt_pk_bf16_f32 v2, v0, s0
	v_lshl_add_u64 v[0:1], v[30:31], 0, v[16:17]
	global_store_short v[0:1], v2, off
	v_mul_f32_e32 v0, v3, v39
	v_cvt_pk_bf16_f32 v2, v0, s0
	v_lshl_add_u64 v[0:1], v[30:31], 0, v[18:19]
	global_store_short v[0:1], v2, off
	v_mul_f32_e32 v0, v4, v40
	v_cvt_pk_bf16_f32 v2, v0, s0
	v_lshl_add_u64 v[0:1], v[30:31], 0, v[48:49]
	global_store_short v[0:1], v2, off
	v_mul_f32_e32 v0, v5, v41
	v_cvt_pk_bf16_f32 v2, v0, s0
	v_lshl_add_u64 v[0:1], v[30:31], 0, v[20:21]
	global_store_short v[0:1], v2, off
	v_mul_f32_e32 v0, v6, v42
	v_cvt_pk_bf16_f32 v2, v0, s0
	v_lshl_add_u64 v[0:1], v[30:31], 0, v[50:51]
	global_store_short v[0:1], v2, off
	v_mul_f32_e32 v0, v7, v43
	v_cvt_pk_bf16_f32 v2, v0, s0
	v_lshl_add_u64 v[0:1], v[30:31], 0, v[22:23]
	global_store_short v[0:1], v2, off
	v_mul_f32_e32 v0, v8, v44
	v_cvt_pk_bf16_f32 v2, v0, s0
	v_lshl_add_u64 v[0:1], v[30:31], 0, v[52:53]
	global_store_short v[0:1], v2, off
	v_mul_f32_e32 v0, v9, v45
	v_cvt_pk_bf16_f32 v2, v0, s0
	v_lshl_add_u64 v[0:1], v[30:31], 0, v[24:25]
	global_store_short v[0:1], v2, off
	v_mul_f32_e32 v0, v10, v46
	v_cvt_pk_bf16_f32 v2, v0, s0
	v_lshl_add_u64 v[0:1], v[30:31], 0, v[54:55]
	global_store_short v[0:1], v2, off
	v_mul_f32_e32 v0, v11, v47
	v_cvt_pk_bf16_f32 v2, v0, s0
	v_lshl_add_u64 v[0:1], v[30:31], 0, v[26:27]
	global_store_short v[0:1], v2, off
	v_mul_f32_e32 v0, v12, v62
	v_cvt_pk_bf16_f32 v2, v0, s0
	v_lshl_add_u64 v[0:1], v[30:31], 0, v[56:57]
	global_store_short v[0:1], v2, off
	v_mul_f32_e32 v0, v13, v63
	v_cvt_pk_bf16_f32 v2, v0, s0
	v_lshl_add_u64 v[0:1], v[30:31], 0, v[28:29]
	global_store_short v[0:1], v2, off
	v_mul_f32_e32 v0, v14, v64
	v_cvt_pk_bf16_f32 v2, v0, s0
	v_lshl_add_u64 v[0:1], v[30:31], 0, v[58:59]
	global_store_short v[0:1], v2, off
	v_mul_f32_e32 v0, v15, v65
	v_cvt_pk_bf16_f32 v2, v0, s0
	v_lshl_add_u64 v[0:1], v[30:31], 0, v[184:185]
	s_and_b64 vcc, exec, s[28:29]
	global_store_short v[0:1], v2, off
	s_cbranch_vccnz .LBB0_560
